# FFN-up GEMM: conv weight/bias slices of the tile prefetched to LDS by a second LDS-DMA load; epilogue reads them from LDS
# speedup vs baseline: 1.0355x; 1.0152x over previous
;     __device__ __forceinline__ void operator()(AccRef acc, const Unit& u, int wr, int wc, int fr, int fq) const {
;     ...
;                 const float rs = rsqrtf(ssq_sum<4>(ssqx + (size_t)(row0 + ai * 128 + m * 16) * 4) * (1.0f / DM) + EPS);
;     ...
;             const int cg4 = gcol + 4 * n, cv4 = cg4 + DFF;
;             const f32x4 g0v = *(const f32x4*)(cw + cg4), g1v = *(const f32x4*)(cw + NUP + cg4), g2v = *(const f32x4*)(cw + 2 * NUP + cg4), gbv = *(const f32x4*)(cb + cg4);
;             const f32x4 h0v = *(const f32x4*)(cw + cv4), h1v = *(const f32x4*)(cw + NUP + cv4), h2v = *(const f32x4*)(cw + 2 * NUP + cv4), hbv = *(const f32x4*)(cb + cv4);
.LBB0_790:
	s_andn2_b64 vcc, exec, s[10:11]
	s_cbranch_vccnz .LBB0_793
	s_cmp_lg_u32 s54, 1
	s_cbranch_scc1 .Lup_ssq_skip
	v_lshl_add_u32 v144, s21, 8, v208
	v_mov_b32_e32 v145, 0
	v_subrev_u32_e32 v144, 0x100, v144
	v_readfirstlane_b32 s46, v208
	v_lshl_add_u64 v[144:145], v[144:145], 4, s[56:57]
	s_nop 1
	s_lshl_b32 s46, s46, 4
	s_add_i32 s46, s46, 0x20400
	s_mov_b32 m0, s46
	s_nop 0
	global_load_lds_dwordx4 v[144:145], off
	v_readfirstlane_b32 s46, v208
	v_and_b32_e32 v148, 32, v208
	v_and_b32_e32 v146, 31, v208
	s_lshl_b32 vcc_lo, s20, 9
	s_bfe_u32 s47, s46, 0x20006
	s_bitcmp1_b32 s47, 1
	s_cselect_b32 vcc_hi, 0x2c00, 0
	s_add_i32 vcc_lo, vcc_lo, vcc_hi
	s_lshl_b32 vcc_hi, s47, 10
	s_add_i32 vcc_hi, vcc_hi, 0x22400
	s_bitcmp1_b32 s47, 0
	s_cselect_b32 s24, s38, s62
	s_cselect_b32 s25, s39, s63
	s_cselect_b32 s46, s76, s70
	s_cselect_b32 s47, s77, s71
	v_mov_b32_e32 v144, s24
	v_mov_b32_e32 v145, s25
	v_cmp_ne_u32_e64 s[24:25], 0, v148
	v_mov_b32_e32 v149, s46
	v_mov_b32_e32 v150, s47
	v_lshlrev_b32_e32 v146, 4, v146
	v_cndmask_b32_e64 v144, v144, v149, s[24:25]
	v_cndmask_b32_e64 v145, v145, v150, s[24:25]
	v_add_u32_e32 v146, vcc_lo, v146
	v_mov_b32_e32 v147, 0
	s_mov_b32 m0, vcc_hi
	v_lshl_add_u64 v[144:145], v[144:145], 0, v[146:147]
	global_load_lds_dwordx4 v[144:145], off

; #define CONV_TAP(t, u, g, ctl) asm("v_fmac_f32_dpp %0, %1, %2 " ctl " row_mask:0xf bank_mask:0xf bound_ctrl:0" : "+v"(t) : "v"(u), "v"(g))
;     __device__ __forceinline__ void operator()(AccRef acc, const Unit& u, int wr, int wc, int fr, int fq) const {
;     ...
;             for (int m = 0; m < 4; ++m) {
;                 const float rs = rsqrtf(ssq_sum<4>(ssqx + (size_t)(row0 + ai * 128 + m * 16) * 4) * (1.0f / DM) + EPS);
; #pragma unroll
;                 for (int bj = 0; bj < 2; ++bj) { acc[ai][bj][m][0] = acc[ai][bj][m][0] * rs; acc[ai][bj][m][1] = acc[ai][bj][m][1] * rs; }
;     ...
;         for (int n = 0; n < 2; ++n) {
;             const int cg4 = gcol + 4 * n, cv4 = cg4 + DFF;
;             const f32x4 g0v = *(const f32x4*)(cw + cg4), g1v = *(const f32x4*)(cw + NUP + cg4), g2v = *(const f32x4*)(cw + 2 * NUP + cg4), gbv = *(const f32x4*)(cb + cg4);
;             const f32x4 h0v = *(const f32x4*)(cw + cv4), h1v = *(const f32x4*)(cw + NUP + cv4), h2v = *(const f32x4*)(cw + 2 * NUP + cv4), hbv = *(const f32x4*)(cb + cv4);
; #pragma unroll
;             for (int ai = 0; ai < 2; ++ai) {
;                 unsigned wpk[4][2]; float rlo[4];
; #pragma unroll
;                 for (int i = 0; i < 4; ++i) {
;                     const float g0 = g0v[i], g1 = g1v[i], g2 = g2v[i], gb = gbv[i], h0 = h0v[i], h1 = h1v[i], h2 = h2v[i], hb = hbv[i];
;                     float gt[4], vl[4];
; #pragma unroll
;                     for (int m = 0; m < 4; ++m) { gt[m] = __builtin_fmaf(g1, acc[ai][0][m][n][i], gb); vl[m] = __builtin_fmaf(h1, acc[ai][1][m][n][i], hb); }
; #pragma unroll
;                     for (int m = 0; m < 4; ++m) {
;                         CONV_TAP(gt[m], acc[ai][0][m][n][i], g0, "row_shr:1"); CONV_TAP(gt[m], acc[ai][0][m][n][i], g2, "row_shl:1");
;                         CONV_TAP(vl[m], acc[ai][1][m][n][i], h0, "row_shr:1"); CONV_TAP(vl[m], acc[ai][1][m][n][i], h2, "row_shl:1");
.LBB0_803:
	s_or_b64 exec, exec, s[24:25]
	s_nop 0
	v_mul_f32_e32 v70, 0x4b800000, v118
	v_cndmask_b32_e64 v70, v118, v70, s[50:51]
	v_rsq_f32_e32 v70, v70
	s_nop 0
	v_mul_f32_e32 v71, 0x45800000, v70
	v_cndmask_b32_e64 v70, v70, v71, s[50:51]
	v_pk_mul_f32 v[154:155], v[56:57], v[70:71] op_sel_hi:[1,0]
	v_mul_f32_e32 v56, 0x4b800000, v85
	v_cndmask_b32_e64 v56, v85, v56, s[52:53]
	v_rsq_f32_e32 v56, v56
	v_pk_mul_f32 v[178:179], v[54:55], v[70:71] op_sel_hi:[1,0]
	v_pk_mul_f32 v[174:175], v[62:63], v[70:71] op_sel_hi:[1,0]
	v_pk_mul_f32 v[118:119], v[64:65], v[70:71] op_sel_hi:[1,0]
	v_mul_f32_e32 v54, 0x45800000, v56
	v_cndmask_b32_e64 v54, v56, v54, s[52:53]
	v_pk_mul_f32 v[156:157], v[40:41], v[54:55] op_sel_hi:[1,0]
	v_mul_f32_e32 v40, 0x4b800000, v180
	v_cndmask_b32_e64 v40, v180, v40, s[46:47]
	v_rsq_f32_e32 v40, v40
	v_pk_mul_f32 v[180:181], v[38:39], v[54:55] op_sel_hi:[1,0]
	v_pk_mul_f32 v[60:61], v[60:61], v[70:71] op_sel_hi:[1,0]
	v_pk_mul_f32 v[58:59], v[58:59], v[70:71] op_sel_hi:[1,0]
	v_mul_f32_e32 v38, 0x45800000, v40
	v_cndmask_b32_e64 v40, v40, v38, s[46:47]
	v_pk_mul_f32 v[194:195], v[24:25], v[40:41] op_sel_hi:[1,0]
	v_mul_f32_e32 v24, 0x4b800000, v193
	v_cndmask_b32_e64 v24, v193, v24, s[48:49]
	v_rsq_f32_e32 v24, v24
	v_pk_mul_f32 v[62:63], v[18:19], v[40:41] op_sel_hi:[1,0]
	v_pk_mul_f32 v[52:53], v[52:53], v[70:71] op_sel_hi:[1,0]
	v_pk_mul_f32 v[50:51], v[50:51], v[70:71] op_sel_hi:[1,0]
	v_mul_f32_e32 v18, 0x45800000, v24
	v_cndmask_b32_e64 v18, v24, v18, s[48:49]
	v_pk_mul_f32 v[120:121], v[48:49], v[54:55] op_sel_hi:[1,0]
	v_pk_mul_f32 v[176:177], v[46:47], v[54:55] op_sel_hi:[1,0]
	v_pk_mul_f32 v[44:45], v[44:45], v[54:55] op_sel_hi:[1,0]
	v_pk_mul_f32 v[42:43], v[42:43], v[54:55] op_sel_hi:[1,0]
	v_pk_mul_f32 v[36:37], v[36:37], v[54:55] op_sel_hi:[1,0]
	v_pk_mul_f32 v[34:35], v[34:35], v[54:55] op_sel_hi:[1,0]
	v_pk_mul_f32 v[190:191], v[32:33], v[40:41] op_sel_hi:[1,0]
	v_pk_mul_f32 v[198:199], v[30:31], v[40:41] op_sel_hi:[1,0]
	v_pk_mul_f32 v[38:39], v[28:29], v[40:41] op_sel_hi:[1,0]
	v_pk_mul_f32 v[54:55], v[26:27], v[40:41] op_sel_hi:[1,0]
	v_pk_mul_f32 v[226:227], v[22:23], v[40:41] op_sel_hi:[1,0]
	v_pk_mul_f32 v[48:49], v[20:21], v[40:41] op_sel_hi:[1,0]
	v_pk_mul_f32 v[192:193], v[16:17], v[18:19] op_sel_hi:[1,0]
	v_pk_mul_f32 v[200:201], v[14:15], v[18:19] op_sel_hi:[1,0]
	v_pk_mul_f32 v[40:41], v[12:13], v[18:19] op_sel_hi:[1,0]
	v_pk_mul_f32 v[56:57], v[10:11], v[18:19] op_sel_hi:[1,0]
	v_pk_mul_f32 v[196:197], v[8:9], v[18:19] op_sel_hi:[1,0]
	v_pk_mul_f32 v[206:207], v[6:7], v[18:19] op_sel_hi:[1,0]
	v_pk_mul_f32 v[46:47], v[4:5], v[18:19] op_sel_hi:[1,0]
	v_pk_mul_f32 v[64:65], v[2:3], v[18:19] op_sel_hi:[1,0]
	v_lshlrev_b64 v[2:3], 2, v[144:145]
	v_and_b32_e32 v70, 0x7f, v144
	v_lshlrev_b32_e32 v70, 2, v70
	v_add_u32_e32 v70, 0x22400, v70
	s_movk_i32 s12, 0x2000
	v_add_co_u32_e32 v78, vcc, s12, v70
	v_lshl_add_u64 v[6:7], s[70:71], 0, v[2:3]
	s_nop 0
	v_addc_co_u32_e32 v79, vcc, 0, v71, vcc
	v_add_co_u32_e32 v84, vcc, s12, v6
	v_lshl_add_u64 v[8:9], s[38:39], 0, v[2:3]
	s_nop 0
	v_addc_co_u32_e32 v85, vcc, 0, v7, vcc
	s_nop 1
	v_lshl_add_u64 v[72:73], s[76:77], 0, v[2:3]
	v_add_co_u32_e32 v86, vcc, s12, v8
	ds_read_b128 v[22:25], v70 offset:512
	ds_read_b128 v[14:17], v70 offset:1024
	ds_read_b128 v[2:5], v70 offset:1536
	v_addc_co_u32_e32 v87, vcc, 0, v9, vcc
	v_add_co_u32_e32 v88, vcc, s12, v72
	ds_read_b128 v[18:21], v70 offset:2048
	ds_read_b128 v[30:33], v70 offset:2560
	v_addc_co_u32_e32 v89, vcc, 0, v73, vcc
	ds_read_b128 v[6:9], v70 offset:3584
	ds_read_b128 v[10:13], v70 offset:0
	ds_read_b128 v[26:29], v70 offset:3072
	s_movk_i32 s12, 0x1600
	s_and_b64 vcc, exec, s[44:45]
	s_waitcnt lgkmcnt(0)
	v_fma_f32 v232, v22, v182, v2
	v_fmac_f32_dpp v232, v182, v10 row_shr:1 row_mask:0xf bank_mask:0xf bound_ctrl:0
	v_fma_f32 v228, v22, v198, v2
	v_fmac_f32_dpp v232, v182, v14 row_shl:1 row_mask:0xf bank_mask:0xf bound_ctrl:0
	v_fmac_f32_dpp v228, v198, v10 row_shr:1 row_mask:0xf bank_mask:0xf bound_ctrl:0
	v_fma_f32 v204, v22, v200, v2
	v_fmac_f32_dpp v232, v198, v14 row_shr:15 row_mask:0xf bank_mask:0xf bound_ctrl:0
	v_fmac_f32_dpp v228, v198, v14 row_shl:1 row_mask:0xf bank_mask:0xf bound_ctrl:0
	v_fmac_f32_dpp v204, v200, v10 row_shr:1 row_mask:0xf bank_mask:0xf bound_ctrl:0
	v_fma_f32 v224, v30, v226, v6
	v_mul_f32_e32 v103, 0xbfb8aa3b, v232
	v_fma_f32 v230, v30, v184, v6
	v_fmac_f32_dpp v224, v226, v18 row_shr:1 row_mask:0xf bank_mask:0xf bound_ctrl:0
	v_exp_f32_e32 v103, v103
	v_fmac_f32_dpp v230, v184, v18 row_shr:1 row_mask:0xf bank_mask:0xf bound_ctrl:0
	v_fmac_f32_dpp v224, v226, v26 row_shl:1 row_mask:0xf bank_mask:0xf bound_ctrl:0
	v_fmac_f32_dpp v228, v182, v10 row_shl:15 row_mask:0xf bank_mask:0xf bound_ctrl:0
	v_fmac_f32_dpp v204, v200, v14 row_shl:1 row_mask:0xf bank_mask:0xf bound_ctrl:0
	v_fma_f32 v202, v30, v206, v6
	v_fmac_f32_dpp v230, v184, v26 row_shl:1 row_mask:0xf bank_mask:0xf bound_ctrl:0
	v_fmac_f32_dpp v224, v184, v18 row_shl:15 row_mask:0xf bank_mask:0xf bound_ctrl:0
	v_fma_f32 v184, v22, v186, v2
	v_fmac_f32_dpp v184, v186, v10 row_shr:1 row_mask:0xf bank_mask:0xf bound_ctrl:0
	v_add_f32_e32 v103, 1.0, v103
	v_fmac_f32_dpp v184, v186, v14 row_shl:1 row_mask:0xf bank_mask:0xf bound_ctrl:0
	v_fmac_f32_dpp v228, v200, v14 row_shr:15 row_mask:0xf bank_mask:0xf bound_ctrl:0
	v_fmac_f32_dpp v204, v198, v10 row_shl:15 row_mask:0xf bank_mask:0xf bound_ctrl:0
	v_fmac_f32_dpp v202, v206, v18 row_shr:1 row_mask:0xf bank_mask:0xf bound_ctrl:0
	v_fma_f32 v182, v30, v188, v6
	v_fmac_f32_dpp v184, v200, v10 row_shl:15 row_mask:0xf bank_mask:0xf bound_ctrl:0
; __device__ __forceinline__ unsigned cvtpk(float lo, float hi) { f32x2 v = {lo, hi}; bf16x2_t b = __builtin_convertvector(v, bf16x2_t); return __builtin_bit_cast(unsigned, b); }
; __device__ __forceinline__ float fast_exp2(float x) { return __builtin_amdgcn_exp2f(x); }
; __device__ __forceinline__ float fast_rcp(float x) { return __builtin_amdgcn_rcpf(x); }
; #define CONV_TAP(t, u, g, ctl) asm("v_fmac_f32_dpp %0, %1, %2 " ctl " row_mask:0xf bank_mask:0xf bound_ctrl:0" : "+v"(t) : "v"(u), "v"(g))
;     __device__ __forceinline__ void operator()(AccRef acc, const Unit& u, int wr, int wc, int fr, int fq) const {
;     ...
;                 for (int i = 0; i < 4; ++i) {
;                     const float g0 = g0v[i], g1 = g1v[i], g2 = g2v[i], gb = gbv[i], h0 = h0v[i], h1 = h1v[i], h2 = h2v[i], hb = hbv[i];
;                     float gt[4], vl[4];
; #pragma unroll
;                     for (int m = 0; m < 4; ++m) { gt[m] = __builtin_fmaf(g1, acc[ai][0][m][n][i], gb); vl[m] = __builtin_fmaf(h1, acc[ai][1][m][n][i], hb); }
; #pragma unroll
;                     for (int m = 0; m < 4; ++m) {
;                         CONV_TAP(gt[m], acc[ai][0][m][n][i], g0, "row_shr:1"); CONV_TAP(gt[m], acc[ai][0][m][n][i], g2, "row_shl:1");
;                         CONV_TAP(vl[m], acc[ai][1][m][n][i], h0, "row_shr:1"); CONV_TAP(vl[m], acc[ai][1][m][n][i], h2, "row_shl:1");
;                         if (m > 0) { CONV_TAP(gt[m], acc[ai][0][m - 1][n][i], g0, "row_shl:15"); CONV_TAP(vl[m], acc[ai][1][m - 1][n][i], h0, "row_shl:15"); }
;                         if (m < 3) { CONV_TAP(gt[m], acc[ai][0][m + 1][n][i], g2, "row_shr:15"); CONV_TAP(vl[m], acc[ai][1][m + 1][n][i], h2, "row_shr:15"); }
;                     }
; #pragma unroll
;                     for (int m = 0; m < 4; ++m) {
;                         const float sg = gt[m] * fast_rcp(1.f + fast_exp2(-LOG2E * gt[m]));
;                         const float rv = sg * vl[m];
;                         if (i & 1) wpk[m][i >> 1] = cvtpk(rlo[m], rv); else rlo[m] = rv;
;                     }
;                     asm volatile("" ::: "memory");
	v_rcp_f32_e32 v200, v103
	v_mul_f32_e32 v103, 0xbfb8aa3b, v228
	v_exp_f32_e32 v103, v103
	v_fmac_f32_dpp v204, v186, v14 row_shr:15 row_mask:0xf bank_mask:0xf bound_ctrl:0
	v_fmac_f32_dpp v202, v206, v26 row_shl:1 row_mask:0xf bank_mask:0xf bound_ctrl:0
	v_fmac_f32_dpp v182, v188, v18 row_shr:1 row_mask:0xf bank_mask:0xf bound_ctrl:0
	v_fma_f32 v233, v23, v183, v3
	v_add_f32_e32 v103, 1.0, v103
	v_rcp_f32_e32 v198, v103
	v_mul_f32_e32 v103, 0xbfb8aa3b, v204
	v_exp_f32_e32 v103, v103
	v_fmac_f32_dpp v202, v226, v18 row_shl:15 row_mask:0xf bank_mask:0xf bound_ctrl:0
	v_fmac_f32_dpp v182, v188, v26 row_shl:1 row_mask:0xf bank_mask:0xf bound_ctrl:0
	v_fmac_f32_dpp v233, v183, v11 row_shr:1 row_mask:0xf bank_mask:0xf bound_ctrl:0
	v_fma_f32 v225, v31, v227, v7
	v_add_f32_e32 v103, 1.0, v103
	v_fmac_f32_dpp v202, v188, v26 row_shr:15 row_mask:0xf bank_mask:0xf bound_ctrl:0
	v_rcp_f32_e32 v188, v103
	v_mul_f32_e32 v103, 0xbfb8aa3b, v184
	v_exp_f32_e32 v103, v103
	v_fmac_f32_dpp v233, v183, v15 row_shl:1 row_mask:0xf bank_mask:0xf bound_ctrl:0
	v_fma_f32 v231, v31, v185, v7
	v_fmac_f32_dpp v233, v199, v15 row_shr:15 row_mask:0xf bank_mask:0xf bound_ctrl:0
	v_add_f32_e32 v103, 1.0, v103
	v_rcp_f32_e32 v186, v103
	v_mul_f32_e32 v103, 0xbfb8aa3b, v233
	v_fmac_f32_dpp v225, v227, v19 row_shr:1 row_mask:0xf bank_mask:0xf bound_ctrl:0
	v_exp_f32_e32 v103, v103
	v_fmac_f32_dpp v231, v185, v19 row_shr:1 row_mask:0xf bank_mask:0xf bound_ctrl:0
	v_fma_f32 v229, v23, v199, v3
	v_fmac_f32_dpp v225, v227, v27 row_shl:1 row_mask:0xf bank_mask:0xf bound_ctrl:0
	v_fmac_f32_dpp v231, v185, v27 row_shl:1 row_mask:0xf bank_mask:0xf bound_ctrl:0
	v_fmac_f32_dpp v229, v199, v11 row_shr:1 row_mask:0xf bank_mask:0xf bound_ctrl:0
	v_fma_f32 v205, v23, v201, v3
	v_fmac_f32_dpp v225, v185, v19 row_shl:15 row_mask:0xf bank_mask:0xf bound_ctrl:0
	v_fma_f32 v185, v23, v187, v3
	v_fmac_f32_dpp v229, v199, v15 row_shl:1 row_mask:0xf bank_mask:0xf bound_ctrl:0
	v_fmac_f32_dpp v185, v187, v11 row_shr:1 row_mask:0xf bank_mask:0xf bound_ctrl:0
	v_fmac_f32_dpp v205, v201, v11 row_shr:1 row_mask:0xf bank_mask:0xf bound_ctrl:0
	v_add_f32_e32 v103, 1.0, v103
	v_fmac_f32_dpp v229, v183, v11 row_shl:15 row_mask:0xf bank_mask:0xf bound_ctrl:0
	v_fmac_f32_dpp v185, v187, v15 row_shl:1 row_mask:0xf bank_mask:0xf bound_ctrl:0
	v_fmac_f32_dpp v205, v201, v15 row_shl:1 row_mask:0xf bank_mask:0xf bound_ctrl:0
	v_fma_f32 v203, v31, v207, v7
	v_fmac_f32_dpp v229, v201, v15 row_shr:15 row_mask:0xf bank_mask:0xf bound_ctrl:0
	v_fmac_f32_dpp v185, v201, v11 row_shl:15 row_mask:0xf bank_mask:0xf bound_ctrl:0
	v_rcp_f32_e32 v201, v103
	v_mul_f32_e32 v103, 0xbfb8aa3b, v229
	v_exp_f32_e32 v103, v103
	v_fmac_f32_dpp v205, v199, v11 row_shl:15 row_mask:0xf bank_mask:0xf bound_ctrl:0
	v_fmac_f32_dpp v203, v207, v19 row_shr:1 row_mask:0xf bank_mask:0xf bound_ctrl:0
	v_fma_f32 v183, v31, v189, v7
	v_add_f32_e32 v103, 1.0, v103
	v_fmac_f32_dpp v205, v187, v15 row_shr:15 row_mask:0xf bank_mask:0xf bound_ctrl:0
	v_rcp_f32_e32 v199, v103
	v_mul_f32_e32 v103, 0xbfb8aa3b, v205
	v_exp_f32_e32 v103, v103
	v_fmac_f32_dpp v203, v207, v27 row_shl:1 row_mask:0xf bank_mask:0xf bound_ctrl:0
	v_fmac_f32_dpp v183, v189, v19 row_shr:1 row_mask:0xf bank_mask:0xf bound_ctrl:0
	v_fmac_f32_dpp v224, v206, v26 row_shr:15 row_mask:0xf bank_mask:0xf bound_ctrl:0
	v_fmac_f32_dpp v182, v206, v18 row_shl:15 row_mask:0xf bank_mask:0xf bound_ctrl:0
	v_fma_f32 v206, v24, v158, v4
	v_fmac_f32_dpp v203, v227, v19 row_shl:15 row_mask:0xf bank_mask:0xf bound_ctrl:0
	v_add_f32_e32 v103, 1.0, v103
	v_fmac_f32_dpp v203, v189, v27 row_shr:15 row_mask:0xf bank_mask:0xf bound_ctrl:0
	v_fmac_f32_dpp v183, v189, v27 row_shl:1 row_mask:0xf bank_mask:0xf bound_ctrl:0
	v_rcp_f32_e32 v189, v103
	v_mul_f32_e32 v103, 0xbfb8aa3b, v185
	v_exp_f32_e32 v103, v103
	v_fmac_f32_dpp v206, v158, v12 row_shr:1 row_mask:0xf bank_mask:0xf bound_ctrl:0
	v_pk_mul_f32 v[188:189], v[204:205], v[188:189]
	v_fmac_f32_dpp v206, v158, v16 row_shl:1 row_mask:0xf bank_mask:0xf bound_ctrl:0
	v_add_f32_e32 v103, 1.0, v103
	v_rcp_f32_e32 v187, v103
	v_fmac_f32_dpp v206, v190, v16 row_shr:15 row_mask:0xf bank_mask:0xf bound_ctrl:0
	v_pk_mul_f32 v[188:189], v[202:203], v[188:189]
	v_mul_f32_e32 v103, 0xbfb8aa3b, v206
	v_pk_mul_f32 v[184:185], v[184:185], v[186:187]
	v_fma_f32 v186, v24, v190, v4
	v_exp_f32_e32 v103, v103
	v_fmac_f32_dpp v186, v190, v12 row_shr:1 row_mask:0xf bank_mask:0xf bound_ctrl:0
	v_fma_f32 v202, v32, v196, v8
	v_fmac_f32_dpp v186, v190, v16 row_shl:1 row_mask:0xf bank_mask:0xf bound_ctrl:0
	v_fmac_f32_dpp v202, v196, v20 row_shr:1 row_mask:0xf bank_mask:0xf bound_ctrl:0
	v_add_f32_e32 v103, 1.0, v103
	v_fmac_f32_dpp v186, v158, v12 row_shl:15 row_mask:0xf bank_mask:0xf bound_ctrl:0
	v_fmac_f32_dpp v202, v196, v28 row_shl:1 row_mask:0xf bank_mask:0xf bound_ctrl:0
	v_fma_f32 v158, v32, v170, v8
	v_fmac_f32_dpp v202, v194, v20 row_shl:15 row_mask:0xf bank_mask:0xf bound_ctrl:0
	v_fmac_f32_dpp v158, v170, v20 row_shr:1 row_mask:0xf bank_mask:0xf bound_ctrl:0
	v_fmac_f32_dpp v186, v192, v16 row_shr:15 row_mask:0xf bank_mask:0xf bound_ctrl:0
	v_fma_f32 v204, v24, v192, v4
	v_fmac_f32_dpp v202, v170, v28 row_shr:15 row_mask:0xf bank_mask:0xf bound_ctrl:0
	v_fmac_f32_dpp v158, v170, v28 row_shl:1 row_mask:0xf bank_mask:0xf bound_ctrl:0
	v_rcp_f32_e32 v170, v103
	v_mul_f32_e32 v103, 0xbfb8aa3b, v186
	v_exp_f32_e32 v103, v103
	v_fmac_f32_dpp v204, v192, v12 row_shr:1 row_mask:0xf bank_mask:0xf bound_ctrl:0
	v_fmac_f32_dpp v183, v207, v19 row_shl:15 row_mask:0xf bank_mask:0xf bound_ctrl:0
	v_pk_mul_f32 v[198:199], v[228:229], v[198:199]
; __device__ __forceinline__ unsigned cvtpk(float lo, float hi) { f32x2 v = {lo, hi}; bf16x2_t b = __builtin_convertvector(v, bf16x2_t); return __builtin_bit_cast(unsigned, b); }
; __device__ __forceinline__ float fast_exp2(float x) { return __builtin_amdgcn_exp2f(x); }
; __device__ __forceinline__ float fast_rcp(float x) { return __builtin_amdgcn_rcpf(x); }
; #define CONV_TAP(t, u, g, ctl) asm("v_fmac_f32_dpp %0, %1, %2 " ctl " row_mask:0xf bank_mask:0xf bound_ctrl:0" : "+v"(t) : "v"(u), "v"(g))
;     __device__ __forceinline__ void operator()(AccRef acc, const Unit& u, int wr, int wc, int fr, int fq) const {
;     ...
;                 for (int i = 0; i < 4; ++i) {
;                     const float g0 = g0v[i], g1 = g1v[i], g2 = g2v[i], gb = gbv[i], h0 = h0v[i], h1 = h1v[i], h2 = h2v[i], hb = hbv[i];
;                     float gt[4], vl[4];
; #pragma unroll
;                     for (int m = 0; m < 4; ++m) { gt[m] = __builtin_fmaf(g1, acc[ai][0][m][n][i], gb); vl[m] = __builtin_fmaf(h1, acc[ai][1][m][n][i], hb); }
; #pragma unroll
;                     for (int m = 0; m < 4; ++m) {
;                         CONV_TAP(gt[m], acc[ai][0][m][n][i], g0, "row_shr:1"); CONV_TAP(gt[m], acc[ai][0][m][n][i], g2, "row_shl:1");
;                         CONV_TAP(vl[m], acc[ai][1][m][n][i], h0, "row_shr:1"); CONV_TAP(vl[m], acc[ai][1][m][n][i], h2, "row_shl:1");
;                         if (m > 0) { CONV_TAP(gt[m], acc[ai][0][m - 1][n][i], g0, "row_shl:15"); CONV_TAP(vl[m], acc[ai][1][m - 1][n][i], h0, "row_shl:15"); }
;                         if (m < 3) { CONV_TAP(gt[m], acc[ai][0][m + 1][n][i], g2, "row_shr:15"); CONV_TAP(vl[m], acc[ai][1][m + 1][n][i], h2, "row_shr:15"); }
;                     }
; #pragma unroll
;                     for (int m = 0; m < 4; ++m) {
;                         const float sg = gt[m] * fast_rcp(1.f + fast_exp2(-LOG2E * gt[m]));
;                         const float rv = sg * vl[m];
;                         if (i & 1) wpk[m][i >> 1] = cvtpk(rlo[m], rv); else rlo[m] = rv;
;                     }
;                     asm volatile("" ::: "memory");
;                 }
; #pragma unroll
;                 for (int m = 0; m < 4; ++m) { u32x2 w; w.x = wpk[m][0]; w.y = wpk[m][1];
;                     *(u32x2*)(ACT + (size_t)(row0 + ai * 128 + m * 16) * DFF + gcol + 4 * n) = w; }
	v_fmac_f32_dpp v204, v192, v16 row_shl:1 row_mask:0xf bank_mask:0xf bound_ctrl:0
	v_add_f32_e32 v103, 1.0, v103
	v_fmac_f32_dpp v204, v190, v12 row_shl:15 row_mask:0xf bank_mask:0xf bound_ctrl:0
	v_pk_mul_f32 v[182:183], v[182:183], v[184:185]
	v_fma_f32 v184, v32, v194, v8
	v_fmac_f32_dpp v204, v166, v16 row_shr:15 row_mask:0xf bank_mask:0xf bound_ctrl:0
	v_rcp_f32_e32 v190, v103
	v_mul_f32_e32 v103, 0xbfb8aa3b, v204
	v_fmac_f32_dpp v225, v207, v27 row_shr:15 row_mask:0xf bank_mask:0xf bound_ctrl:0
	v_fmac_f32_dpp v184, v194, v20 row_shr:1 row_mask:0xf bank_mask:0xf bound_ctrl:0
	v_exp_f32_e32 v103, v103
	v_pk_mul_f32 v[198:199], v[224:225], v[198:199]
	v_fma_f32 v224, v32, v160, v8
	v_fmac_f32_dpp v224, v160, v20 row_shr:1 row_mask:0xf bank_mask:0xf bound_ctrl:0
	v_fmac_f32_dpp v184, v194, v28 row_shl:1 row_mask:0xf bank_mask:0xf bound_ctrl:0
	v_add_f32_e32 v103, 1.0, v103
	v_fmac_f32_dpp v224, v160, v28 row_shl:1 row_mask:0xf bank_mask:0xf bound_ctrl:0
	v_fmac_f32_dpp v184, v160, v20 row_shl:15 row_mask:0xf bank_mask:0xf bound_ctrl:0
	v_fma_f32 v160, v24, v166, v4
	v_fmac_f32_dpp v160, v166, v12 row_shr:1 row_mask:0xf bank_mask:0xf bound_ctrl:0
	v_fma_f32 v207, v25, v159, v5
	v_fmac_f32_dpp v160, v166, v16 row_shl:1 row_mask:0xf bank_mask:0xf bound_ctrl:0
	v_fmac_f32_dpp v207, v159, v13 row_shr:1 row_mask:0xf bank_mask:0xf bound_ctrl:0
	v_fma_f32 v187, v25, v191, v5
	v_fmac_f32_dpp v160, v192, v12 row_shl:15 row_mask:0xf bank_mask:0xf bound_ctrl:0
	v_rcp_f32_e32 v192, v103
	v_mul_f32_e32 v103, 0xbfb8aa3b, v160
	v_exp_f32_e32 v103, v103
	v_fmac_f32_dpp v207, v159, v17 row_shl:1 row_mask:0xf bank_mask:0xf bound_ctrl:0
	v_fmac_f32_dpp v187, v191, v13 row_shr:1 row_mask:0xf bank_mask:0xf bound_ctrl:0
	v_fma_f32 v203, v33, v197, v9
	v_add_f32_e32 v103, 1.0, v103
	v_rcp_f32_e32 v166, v103
	v_fmac_f32_dpp v207, v191, v17 row_shr:15 row_mask:0xf bank_mask:0xf bound_ctrl:0
	v_fmac_f32_dpp v187, v191, v17 row_shl:1 row_mask:0xf bank_mask:0xf bound_ctrl:0
	v_fmac_f32_dpp v203, v197, v21 row_shr:1 row_mask:0xf bank_mask:0xf bound_ctrl:0
	v_fma_f32 v205, v25, v193, v5
	v_mul_f32_e32 v103, 0xbfb8aa3b, v207
	v_exp_f32_e32 v103, v103
	v_fmac_f32_dpp v187, v159, v13 row_shl:15 row_mask:0xf bank_mask:0xf bound_ctrl:0
	v_fmac_f32_dpp v203, v197, v29 row_shl:1 row_mask:0xf bank_mask:0xf bound_ctrl:0
	v_fma_f32 v159, v33, v171, v9
	v_fmac_f32_dpp v203, v195, v21 row_shl:15 row_mask:0xf bank_mask:0xf bound_ctrl:0
	v_fmac_f32_dpp v159, v171, v21 row_shr:1 row_mask:0xf bank_mask:0xf bound_ctrl:0
	v_add_f32_e32 v103, 1.0, v103
	v_fmac_f32_dpp v187, v193, v17 row_shr:15 row_mask:0xf bank_mask:0xf bound_ctrl:0
	v_fmac_f32_dpp v203, v171, v29 row_shr:15 row_mask:0xf bank_mask:0xf bound_ctrl:0
	v_fmac_f32_dpp v159, v171, v29 row_shl:1 row_mask:0xf bank_mask:0xf bound_ctrl:0
	v_rcp_f32_e32 v171, v103
	v_mul_f32_e32 v103, 0xbfb8aa3b, v187
	v_exp_f32_e32 v103, v103
	v_fmac_f32_dpp v205, v193, v13 row_shr:1 row_mask:0xf bank_mask:0xf bound_ctrl:0
	v_fma_f32 v185, v33, v195, v9
	v_fmac_f32_dpp v205, v193, v17 row_shl:1 row_mask:0xf bank_mask:0xf bound_ctrl:0
	v_add_f32_e32 v103, 1.0, v103
	v_fmac_f32_dpp v205, v191, v13 row_shl:15 row_mask:0xf bank_mask:0xf bound_ctrl:0
	v_rcp_f32_e32 v191, v103
	v_fmac_f32_dpp v205, v167, v17 row_shr:15 row_mask:0xf bank_mask:0xf bound_ctrl:0
	v_fma_f32 v225, v33, v161, v9
	v_mul_f32_e32 v103, 0xbfb8aa3b, v205
	v_fmac_f32_dpp v185, v195, v21 row_shr:1 row_mask:0xf bank_mask:0xf bound_ctrl:0
	v_exp_f32_e32 v103, v103
	v_fmac_f32_dpp v225, v161, v21 row_shr:1 row_mask:0xf bank_mask:0xf bound_ctrl:0
	v_fmac_f32_dpp v185, v195, v29 row_shl:1 row_mask:0xf bank_mask:0xf bound_ctrl:0
	v_fmac_f32_dpp v158, v196, v20 row_shl:15 row_mask:0xf bank_mask:0xf bound_ctrl:0
	v_fmac_f32_dpp v159, v197, v21 row_shl:15 row_mask:0xf bank_mask:0xf bound_ctrl:0
	v_pk_mul_f32 v[200:201], v[232:233], v[200:201]
	v_fmac_f32_dpp v225, v161, v29 row_shl:1 row_mask:0xf bank_mask:0xf bound_ctrl:0
	v_fmac_f32_dpp v185, v161, v21 row_shl:15 row_mask:0xf bank_mask:0xf bound_ctrl:0
	v_fma_f32 v161, v25, v167, v5
	v_fmac_f32_dpp v161, v167, v13 row_shr:1 row_mask:0xf bank_mask:0xf bound_ctrl:0
	v_add_f32_e32 v103, 1.0, v103
	v_fmac_f32_dpp v161, v167, v17 row_shl:1 row_mask:0xf bank_mask:0xf bound_ctrl:0
	v_cvt_pk_bf16_f32 v182, v182, v183
	v_fmac_f32_dpp v161, v193, v13 row_shl:15 row_mask:0xf bank_mask:0xf bound_ctrl:0
	v_rcp_f32_e32 v193, v103
	v_mul_f32_e32 v103, 0xbfb8aa3b, v161
	v_exp_f32_e32 v103, v103
	v_pk_mul_f32 v[170:171], v[206:207], v[170:171]
	v_fmac_f32_dpp v230, v226, v26 row_shr:15 row_mask:0xf bank_mask:0xf bound_ctrl:0
	v_fmac_f32_dpp v231, v227, v27 row_shr:15 row_mask:0xf bank_mask:0xf bound_ctrl:0
	v_add_f32_e32 v103, 1.0, v103
	v_rcp_f32_e32 v167, v103
	v_pk_mul_f32 v[200:201], v[230:231], v[200:201]
	v_fmac_f32_dpp v224, v194, v28 row_shr:15 row_mask:0xf bank_mask:0xf bound_ctrl:0
	v_fmac_f32_dpp v225, v195, v29 row_shr:15 row_mask:0xf bank_mask:0xf bound_ctrl:0
	v_pk_mul_f32 v[160:161], v[160:161], v[166:167]
	v_pk_mul_f32 v[170:171], v[224:225], v[170:171]
	v_pk_mul_f32 v[158:159], v[158:159], v[160:161]
	v_lshlrev_b64 v[160:161], 1, v[144:145]
	v_cvt_pk_bf16_f32 v183, v158, v159
	v_mov_b64_e32 v[158:159], s[90:91]
	v_mad_i64_i32 v[152:153], s[20:21], v152, s12, v[158:159]
	v_cvt_pk_bf16_f32 v200, v200, v201
	v_cvt_pk_bf16_f32 v201, v170, v171
	v_pk_mul_f32 v[170:171], v[186:187], v[190:191]
	v_lshl_add_u64 v[152:153], v[152:153], 0, v[160:161]
	v_fmac_f32_dpp v184, v196, v28 row_shr:15 row_mask:0xf bank_mask:0xf bound_ctrl:0
	v_fmac_f32_dpp v185, v197, v29 row_shr:15 row_mask:0xf bank_mask:0xf bound_ctrl:0
	global_store_dwordx2 v[152:153], v[182:183], off
; __device__ __forceinline__ unsigned cvtpk(float lo, float hi) { f32x2 v = {lo, hi}; bf16x2_t b = __builtin_convertvector(v, bf16x2_t); return __builtin_bit_cast(unsigned, b); }
; __device__ __forceinline__ float fast_exp2(float x) { return __builtin_amdgcn_exp2f(x); }
; __device__ __forceinline__ float fast_rcp(float x) { return __builtin_amdgcn_rcpf(x); }
; #define CONV_TAP(t, u, g, ctl) asm("v_fmac_f32_dpp %0, %1, %2 " ctl " row_mask:0xf bank_mask:0xf bound_ctrl:0" : "+v"(t) : "v"(u), "v"(g))
;     __device__ __forceinline__ void operator()(AccRef acc, const Unit& u, int wr, int wc, int fr, int fq) const {
;     ...
;                 for (int i = 0; i < 4; ++i) {
;                     const float g0 = g0v[i], g1 = g1v[i], g2 = g2v[i], gb = gbv[i], h0 = h0v[i], h1 = h1v[i], h2 = h2v[i], hb = hbv[i];
;                     float gt[4], vl[4];
; #pragma unroll
;                     for (int m = 0; m < 4; ++m) { gt[m] = __builtin_fmaf(g1, acc[ai][0][m][n][i], gb); vl[m] = __builtin_fmaf(h1, acc[ai][1][m][n][i], hb); }
; #pragma unroll
;                     for (int m = 0; m < 4; ++m) {
;                         CONV_TAP(gt[m], acc[ai][0][m][n][i], g0, "row_shr:1"); CONV_TAP(gt[m], acc[ai][0][m][n][i], g2, "row_shl:1");
;                         CONV_TAP(vl[m], acc[ai][1][m][n][i], h0, "row_shr:1"); CONV_TAP(vl[m], acc[ai][1][m][n][i], h2, "row_shl:1");
;                         if (m > 0) { CONV_TAP(gt[m], acc[ai][0][m - 1][n][i], g0, "row_shl:15"); CONV_TAP(vl[m], acc[ai][1][m - 1][n][i], h0, "row_shl:15"); }
;                         if (m < 3) { CONV_TAP(gt[m], acc[ai][0][m + 1][n][i], g2, "row_shr:15"); CONV_TAP(vl[m], acc[ai][1][m + 1][n][i], h2, "row_shr:15"); }
;                     }
; #pragma unroll
;                     for (int m = 0; m < 4; ++m) {
;                         const float sg = gt[m] * fast_rcp(1.f + fast_exp2(-LOG2E * gt[m]));
;                         const float rv = sg * vl[m];
;                         if (i & 1) wpk[m][i >> 1] = cvtpk(rlo[m], rv); else rlo[m] = rv;
;                     }
;                     asm volatile("" ::: "memory");
	v_pk_mul_f32 v[170:171], v[184:185], v[170:171]
	v_fma_f32 v182, v22, v162, v2
	v_fma_f32 v166, v30, v178, v6
	v_fma_f32 v183, v23, v163, v3
	v_fma_f32 v167, v31, v179, v7
	v_cvt_pk_bf16_f32 v198, v198, v199
	v_cvt_pk_bf16_f32 v199, v170, v171
	v_pk_mul_f32 v[170:171], v[204:205], v[192:193]
	v_fma_f32 v184, v30, v164, v6
	v_fmac_f32_dpp v182, v162, v10 row_shr:1 row_mask:0xf bank_mask:0xf bound_ctrl:0
	v_fmac_f32_dpp v166, v178, v18 row_shr:1 row_mask:0xf bank_mask:0xf bound_ctrl:0
	v_fma_f32 v185, v31, v165, v7
	v_fmac_f32_dpp v183, v163, v11 row_shr:1 row_mask:0xf bank_mask:0xf bound_ctrl:0
	v_fmac_f32_dpp v167, v179, v19 row_shr:1 row_mask:0xf bank_mask:0xf bound_ctrl:0
	v_pk_mul_f32 v[170:171], v[202:203], v[170:171]
	v_fmac_f32_dpp v182, v162, v14 row_shl:1 row_mask:0xf bank_mask:0xf bound_ctrl:0
	v_fmac_f32_dpp v184, v164, v18 row_shr:1 row_mask:0xf bank_mask:0xf bound_ctrl:0
	v_fmac_f32_dpp v166, v178, v26 row_shl:1 row_mask:0xf bank_mask:0xf bound_ctrl:0
	v_fmac_f32_dpp v183, v163, v15 row_shl:1 row_mask:0xf bank_mask:0xf bound_ctrl:0
	v_fmac_f32_dpp v185, v165, v19 row_shr:1 row_mask:0xf bank_mask:0xf bound_ctrl:0
	v_fmac_f32_dpp v167, v179, v27 row_shl:1 row_mask:0xf bank_mask:0xf bound_ctrl:0
	v_cvt_pk_bf16_f32 v188, v188, v189
	v_cvt_pk_bf16_f32 v189, v170, v171
	v_fmac_f32_dpp v184, v164, v26 row_shl:1 row_mask:0xf bank_mask:0xf bound_ctrl:0
	v_fmac_f32_dpp v182, v174, v14 row_shr:15 row_mask:0xf bank_mask:0xf bound_ctrl:0
	v_fma_f32 v170, v22, v174, v2
	v_fmac_f32_dpp v166, v164, v18 row_shl:15 row_mask:0xf bank_mask:0xf bound_ctrl:0
	v_fma_f32 v164, v22, v176, v2
	v_fma_f32 v22, v22, v168, v2
	v_mul_f32_e32 v2, 0xbfb8aa3b, v182
	v_fmac_f32_dpp v185, v165, v27 row_shl:1 row_mask:0xf bank_mask:0xf bound_ctrl:0
	v_fmac_f32_dpp v183, v175, v15 row_shr:15 row_mask:0xf bank_mask:0xf bound_ctrl:0
	v_fma_f32 v171, v23, v175, v3
	v_fmac_f32_dpp v167, v165, v19 row_shl:15 row_mask:0xf bank_mask:0xf bound_ctrl:0
	v_fma_f32 v165, v23, v177, v3
	v_fma_f32 v23, v23, v169, v3
	v_mul_f32_e32 v3, 0xbfb8aa3b, v183
	v_exp_f32_e32 v2, v2
	v_exp_f32_e32 v3, v3
	v_fmac_f32_dpp v171, v175, v11 row_shr:1 row_mask:0xf bank_mask:0xf bound_ctrl:0
	v_fmac_f32_dpp v184, v178, v26 row_shr:15 row_mask:0xf bank_mask:0xf bound_ctrl:0
	v_add_f32_e32 v2, 1.0, v2
	v_add_f32_e32 v3, 1.0, v3
	v_rcp_f32_e32 v2, v2
	v_rcp_f32_e32 v3, v3
	v_fmac_f32_dpp v171, v175, v15 row_shl:1 row_mask:0xf bank_mask:0xf bound_ctrl:0
	v_fmac_f32_dpp v185, v179, v27 row_shr:15 row_mask:0xf bank_mask:0xf bound_ctrl:0
	v_fmac_f32_dpp v165, v177, v11 row_shr:1 row_mask:0xf bank_mask:0xf bound_ctrl:0
	v_fmac_f32_dpp v164, v176, v10 row_shr:1 row_mask:0xf bank_mask:0xf bound_ctrl:0
	v_fmac_f32_dpp v170, v174, v10 row_shr:1 row_mask:0xf bank_mask:0xf bound_ctrl:0
	s_nop 0
	v_pk_mul_f32 v[2:3], v[182:183], v[2:3]
	v_fmac_f32_dpp v171, v163, v11 row_shl:15 row_mask:0xf bank_mask:0xf bound_ctrl:0
	v_fmac_f32_dpp v165, v177, v15 row_shl:1 row_mask:0xf bank_mask:0xf bound_ctrl:0
	v_fmac_f32_dpp v164, v176, v14 row_shl:1 row_mask:0xf bank_mask:0xf bound_ctrl:0
	v_fmac_f32_dpp v22, v168, v10 row_shr:1 row_mask:0xf bank_mask:0xf bound_ctrl:0
	v_fmac_f32_dpp v170, v174, v14 row_shl:1 row_mask:0xf bank_mask:0xf bound_ctrl:0
	s_nop 0
	v_pk_mul_f32 v[2:3], v[184:185], v[2:3]
	v_fmac_f32_dpp v171, v177, v15 row_shr:15 row_mask:0xf bank_mask:0xf bound_ctrl:0
	v_fmac_f32_dpp v165, v175, v11 row_shl:15 row_mask:0xf bank_mask:0xf bound_ctrl:0
	v_fmac_f32_dpp v164, v174, v10 row_shl:15 row_mask:0xf bank_mask:0xf bound_ctrl:0
	v_fmac_f32_dpp v22, v168, v14 row_shl:1 row_mask:0xf bank_mask:0xf bound_ctrl:0
	v_fma_f32 v163, v31, v181, v7
	v_cvt_pk_bf16_f32 v2, v2, v3
	v_mul_f32_e32 v3, 0xbfb8aa3b, v171
	v_exp_f32_e32 v3, v3
	v_fmac_f32_dpp v165, v169, v15 row_shr:15 row_mask:0xf bank_mask:0xf bound_ctrl:0
	v_fma_f32 v31, v31, v173, v7
	v_fmac_f32_dpp v170, v162, v10 row_shl:15 row_mask:0xf bank_mask:0xf bound_ctrl:0
	v_add_f32_e32 v3, 1.0, v3
	v_rcp_f32_e32 v7, v3
	v_mul_f32_e32 v3, 0xbfb8aa3b, v165
	v_fmac_f32_dpp v164, v168, v14 row_shr:15 row_mask:0xf bank_mask:0xf bound_ctrl:0
	v_fmac_f32_dpp v22, v176, v10 row_shl:15 row_mask:0xf bank_mask:0xf bound_ctrl:0
	v_exp_f32_e32 v3, v3
	v_mul_f32_e32 v10, 0xbfb8aa3b, v164
	v_exp_f32_e32 v10, v10
	v_fmac_f32_dpp v23, v169, v11 row_shr:1 row_mask:0xf bank_mask:0xf bound_ctrl:0
	v_add_f32_e32 v3, 1.0, v3
	v_fmac_f32_dpp v23, v169, v15 row_shl:1 row_mask:0xf bank_mask:0xf bound_ctrl:0
	v_fmac_f32_dpp v170, v176, v14 row_shr:15 row_mask:0xf bank_mask:0xf bound_ctrl:0
	v_add_f32_e32 v10, 1.0, v10
	v_mul_f32_e32 v14, 0xbfb8aa3b, v22
	v_fmac_f32_dpp v23, v177, v11 row_shl:15 row_mask:0xf bank_mask:0xf bound_ctrl:0
	v_rcp_f32_e32 v11, v3
	v_mul_f32_e32 v3, 0xbfb8aa3b, v23
	v_fma_f32 v162, v30, v180, v6
	v_rcp_f32_e32 v10, v10
	v_exp_f32_e32 v14, v14
	v_exp_f32_e32 v3, v3
	v_fmac_f32_dpp v162, v180, v18 row_shr:1 row_mask:0xf bank_mask:0xf bound_ctrl:0
	v_fmac_f32_dpp v163, v181, v19 row_shr:1 row_mask:0xf bank_mask:0xf bound_ctrl:0
	v_add_f32_e32 v14, 1.0, v14
	v_fmac_f32_dpp v162, v180, v26 row_shl:1 row_mask:0xf bank_mask:0xf bound_ctrl:0
	v_fmac_f32_dpp v163, v181, v27 row_shl:1 row_mask:0xf bank_mask:0xf bound_ctrl:0
	v_pk_mul_f32 v[10:11], v[164:165], v[10:11]
	v_fmac_f32_dpp v162, v178, v18 row_shl:15 row_mask:0xf bank_mask:0xf bound_ctrl:0
	v_fmac_f32_dpp v163, v179, v19 row_shl:15 row_mask:0xf bank_mask:0xf bound_ctrl:0
	v_add_f32_e32 v3, 1.0, v3
	v_fmac_f32_dpp v162, v172, v26 row_shr:15 row_mask:0xf bank_mask:0xf bound_ctrl:0
	v_rcp_f32_e32 v14, v14
	v_fmac_f32_dpp v163, v173, v27 row_shr:15 row_mask:0xf bank_mask:0xf bound_ctrl:0
	v_rcp_f32_e32 v15, v3
; __device__ __forceinline__ unsigned cvtpk(float lo, float hi) { f32x2 v = {lo, hi}; bf16x2_t b = __builtin_convertvector(v, bf16x2_t); return __builtin_bit_cast(unsigned, b); }
; __device__ __forceinline__ float fast_exp2(float x) { return __builtin_amdgcn_exp2f(x); }
; __device__ __forceinline__ float fast_rcp(float x) { return __builtin_amdgcn_rcpf(x); }
; #define CONV_TAP(t, u, g, ctl) asm("v_fmac_f32_dpp %0, %1, %2 " ctl " row_mask:0xf bank_mask:0xf bound_ctrl:0" : "+v"(t) : "v"(u), "v"(g))
;     __device__ __forceinline__ void operator()(AccRef acc, const Unit& u, int wr, int wc, int fr, int fq) const {
;     ...
;                 for (int i = 0; i < 4; ++i) {
;                     const float g0 = g0v[i], g1 = g1v[i], g2 = g2v[i], gb = gbv[i], h0 = h0v[i], h1 = h1v[i], h2 = h2v[i], hb = hbv[i];
;                     float gt[4], vl[4];
; #pragma unroll
;                     for (int m = 0; m < 4; ++m) { gt[m] = __builtin_fmaf(g1, acc[ai][0][m][n][i], gb); vl[m] = __builtin_fmaf(h1, acc[ai][1][m][n][i], hb); }
; #pragma unroll
;                     for (int m = 0; m < 4; ++m) {
;                         CONV_TAP(gt[m], acc[ai][0][m][n][i], g0, "row_shr:1"); CONV_TAP(gt[m], acc[ai][0][m][n][i], g2, "row_shl:1");
;                         CONV_TAP(vl[m], acc[ai][1][m][n][i], h0, "row_shr:1"); CONV_TAP(vl[m], acc[ai][1][m][n][i], h2, "row_shl:1");
;                         if (m > 0) { CONV_TAP(gt[m], acc[ai][0][m - 1][n][i], g0, "row_shl:15"); CONV_TAP(vl[m], acc[ai][1][m - 1][n][i], h0, "row_shl:15"); }
;                         if (m < 3) { CONV_TAP(gt[m], acc[ai][0][m + 1][n][i], g2, "row_shr:15"); CONV_TAP(vl[m], acc[ai][1][m + 1][n][i], h2, "row_shr:15"); }
;                     }
; #pragma unroll
;                     for (int m = 0; m < 4; ++m) {
;                         const float sg = gt[m] * fast_rcp(1.f + fast_exp2(-LOG2E * gt[m]));
;                         const float rv = sg * vl[m];
;                         if (i & 1) wpk[m][i >> 1] = cvtpk(rlo[m], rv); else rlo[m] = rv;
;                     }
;                     asm volatile("" ::: "memory");
	v_pk_mul_f32 v[10:11], v[162:163], v[10:11]
	v_fma_f32 v162, v24, v114, v4
	v_fma_f32 v30, v30, v172, v6
	v_fmac_f32_dpp v162, v114, v12 row_shr:1 row_mask:0xf bank_mask:0xf bound_ctrl:0
	v_fmac_f32_dpp v30, v172, v18 row_shr:1 row_mask:0xf bank_mask:0xf bound_ctrl:0
	v_fmac_f32_dpp v31, v173, v19 row_shr:1 row_mask:0xf bank_mask:0xf bound_ctrl:0
	v_pk_mul_f32 v[14:15], v[22:23], v[14:15]
	v_fmac_f32_dpp v162, v114, v16 row_shl:1 row_mask:0xf bank_mask:0xf bound_ctrl:0
	v_fmac_f32_dpp v30, v172, v26 row_shl:1 row_mask:0xf bank_mask:0xf bound_ctrl:0
	v_fmac_f32_dpp v31, v173, v27 row_shl:1 row_mask:0xf bank_mask:0xf bound_ctrl:0
	v_fma_f32 v22, v24, v118, v4
	v_fmac_f32_dpp v162, v118, v16 row_shr:15 row_mask:0xf bank_mask:0xf bound_ctrl:0
	v_fmac_f32_dpp v30, v180, v18 row_shl:15 row_mask:0xf bank_mask:0xf bound_ctrl:0
	v_fmac_f32_dpp v31, v181, v19 row_shl:15 row_mask:0xf bank_mask:0xf bound_ctrl:0
	v_fmac_f32_dpp v22, v118, v12 row_shr:1 row_mask:0xf bank_mask:0xf bound_ctrl:0
	v_fmac_f32_dpp v166, v180, v26 row_shr:15 row_mask:0xf bank_mask:0xf bound_ctrl:0
	v_fma_f32 v164, v32, v116, v8
	v_mul_f32_e32 v3, 0xbfb8aa3b, v162
	v_exp_f32_e32 v3, v3
	v_pk_mul_f32 v[14:15], v[30:31], v[14:15]
	v_fma_f32 v30, v24, v120, v4
	v_fmac_f32_dpp v30, v120, v12 row_shr:1 row_mask:0xf bank_mask:0xf bound_ctrl:0
	v_fmac_f32_dpp v22, v118, v16 row_shl:1 row_mask:0xf bank_mask:0xf bound_ctrl:0
	v_fma_f32 v4, v24, v80, v4
	v_fmac_f32_dpp v30, v120, v16 row_shl:1 row_mask:0xf bank_mask:0xf bound_ctrl:0
	v_fmac_f32_dpp v22, v114, v12 row_shl:15 row_mask:0xf bank_mask:0xf bound_ctrl:0
	v_fmac_f32_dpp v4, v80, v12 row_shr:1 row_mask:0xf bank_mask:0xf bound_ctrl:0
	v_add_f32_e32 v3, 1.0, v3
	v_fmac_f32_dpp v30, v118, v12 row_shl:15 row_mask:0xf bank_mask:0xf bound_ctrl:0
	v_fmac_f32_dpp v22, v120, v16 row_shr:15 row_mask:0xf bank_mask:0xf bound_ctrl:0
	v_fmac_f32_dpp v4, v80, v16 row_shl:1 row_mask:0xf bank_mask:0xf bound_ctrl:0
	v_fma_f32 v18, v32, v154, v8
	v_fmac_f32_dpp v30, v80, v16 row_shr:15 row_mask:0xf bank_mask:0xf bound_ctrl:0
	v_rcp_f32_e32 v16, v3
	v_mul_f32_e32 v3, 0xbfb8aa3b, v22
	v_exp_f32_e32 v3, v3
	v_fma_f32 v26, v32, v156, v8
	v_fma_f32 v8, v32, v82, v8
	v_fmac_f32_dpp v18, v154, v20 row_shr:1 row_mask:0xf bank_mask:0xf bound_ctrl:0
	v_fmac_f32_dpp v26, v156, v20 row_shr:1 row_mask:0xf bank_mask:0xf bound_ctrl:0
	v_fmac_f32_dpp v8, v82, v20 row_shr:1 row_mask:0xf bank_mask:0xf bound_ctrl:0
	v_add_f32_e32 v3, 1.0, v3
	v_fmac_f32_dpp v18, v154, v28 row_shl:1 row_mask:0xf bank_mask:0xf bound_ctrl:0
	v_fmac_f32_dpp v26, v156, v28 row_shl:1 row_mask:0xf bank_mask:0xf bound_ctrl:0
	v_fmac_f32_dpp v8, v82, v28 row_shl:1 row_mask:0xf bank_mask:0xf bound_ctrl:0
	v_fmac_f32_dpp v164, v116, v20 row_shr:1 row_mask:0xf bank_mask:0xf bound_ctrl:0
	v_mul_f32_e32 v6, 0xbfb8aa3b, v170
	v_fmac_f32_dpp v18, v116, v20 row_shl:15 row_mask:0xf bank_mask:0xf bound_ctrl:0
	v_fmac_f32_dpp v26, v154, v20 row_shl:15 row_mask:0xf bank_mask:0xf bound_ctrl:0
	v_fmac_f32_dpp v8, v156, v20 row_shl:15 row_mask:0xf bank_mask:0xf bound_ctrl:0
	v_rcp_f32_e32 v20, v3
	v_mul_f32_e32 v3, 0xbfb8aa3b, v30
	v_exp_f32_e32 v3, v3
	v_exp_f32_e32 v6, v6
	v_fmac_f32_dpp v4, v120, v12 row_shl:15 row_mask:0xf bank_mask:0xf bound_ctrl:0
	v_fma_f32 v163, v25, v115, v5
	v_add_f32_e32 v3, 1.0, v3
	v_rcp_f32_e32 v24, v3
	v_mul_f32_e32 v3, 0xbfb8aa3b, v4
	v_exp_f32_e32 v3, v3
	v_add_f32_e32 v6, 1.0, v6
	v_fma_f32 v23, v25, v119, v5
	v_fma_f32 v31, v25, v121, v5
	v_fmac_f32_e32 v5, v25, v81
	v_rcp_f32_e32 v6, v6
	v_fmac_f32_dpp v23, v119, v13 row_shr:1 row_mask:0xf bank_mask:0xf bound_ctrl:0
	v_fmac_f32_dpp v31, v121, v13 row_shr:1 row_mask:0xf bank_mask:0xf bound_ctrl:0
	v_fmac_f32_dpp v5, v81, v13 row_shr:1 row_mask:0xf bank_mask:0xf bound_ctrl:0
	v_fmac_f32_dpp v163, v115, v13 row_shr:1 row_mask:0xf bank_mask:0xf bound_ctrl:0
	v_add_f32_e32 v3, 1.0, v3
	v_fmac_f32_dpp v23, v119, v17 row_shl:1 row_mask:0xf bank_mask:0xf bound_ctrl:0
	v_fmac_f32_dpp v31, v121, v17 row_shl:1 row_mask:0xf bank_mask:0xf bound_ctrl:0
	v_fmac_f32_dpp v5, v81, v17 row_shl:1 row_mask:0xf bank_mask:0xf bound_ctrl:0
	v_fmac_f32_dpp v163, v115, v17 row_shl:1 row_mask:0xf bank_mask:0xf bound_ctrl:0
	v_rcp_f32_e32 v12, v3
	v_fmac_f32_dpp v23, v115, v13 row_shl:15 row_mask:0xf bank_mask:0xf bound_ctrl:0
	v_fmac_f32_dpp v31, v119, v13 row_shl:15 row_mask:0xf bank_mask:0xf bound_ctrl:0
	v_fmac_f32_dpp v5, v121, v13 row_shl:15 row_mask:0xf bank_mask:0xf bound_ctrl:0
	v_fmac_f32_dpp v163, v119, v17 row_shr:15 row_mask:0xf bank_mask:0xf bound_ctrl:0
	v_pk_mul_f32 v[6:7], v[170:171], v[6:7]
	v_mul_f32_e32 v13, 0xbfb8aa3b, v5
	v_mul_f32_e32 v3, 0xbfb8aa3b, v163
	v_exp_f32_e32 v13, v13
	v_exp_f32_e32 v3, v3
	v_fmac_f32_dpp v167, v181, v27 row_shr:15 row_mask:0xf bank_mask:0xf bound_ctrl:0
	v_fmac_f32_dpp v23, v121, v17 row_shr:15 row_mask:0xf bank_mask:0xf bound_ctrl:0
	v_add_f32_e32 v13, 1.0, v13
	v_pk_mul_f32 v[6:7], v[166:167], v[6:7]
	v_cvt_pk_bf16_f32 v10, v10, v11
	v_cvt_pk_bf16_f32 v6, v6, v7
	v_mul_f32_e32 v7, 0xbfb8aa3b, v23
	v_exp_f32_e32 v7, v7
	v_fmac_f32_dpp v31, v81, v17 row_shr:15 row_mask:0xf bank_mask:0xf bound_ctrl:0
	v_add_f32_e32 v3, 1.0, v3
	v_mul_f32_e32 v11, 0xbfb8aa3b, v31
	v_rcp_f32_e32 v13, v13
	v_mad_i64_i32 v[146:147], s[20:21], v146, s12, v[158:159]
	v_mad_i64_i32 v[148:149], s[20:21], v148, s12, v[158:159]
	v_mad_i64_i32 v[150:151], s[20:21], v150, s12, v[158:159]
	v_fma_f32 v165, v33, v117, v9
	v_fma_f32 v19, v33, v155, v9
	v_fma_f32 v27, v33, v157, v9
	v_fmac_f32_e32 v9, v33, v83
	v_rcp_f32_e32 v17, v3
	v_exp_f32_e32 v11, v11
	v_lshl_add_u64 v[146:147], v[146:147], 0, v[160:161]
;     __device__ __forceinline__ void operator()(AccRef acc, const Unit& u, int wr, int wc, int fr, int fq) const {
;     ...
;             const int cg4 = gcol + 4 * n, cv4 = cg4 + DFF;
;             const f32x4 g0v = *(const f32x4*)(cw + cg4), g1v = *(const f32x4*)(cw + NUP + cg4), g2v = *(const f32x4*)(cw + 2 * NUP + cg4), gbv = *(const f32x4*)(cb + cg4);
;             const f32x4 h0v = *(const f32x4*)(cw + cv4), h1v = *(const f32x4*)(cw + NUP + cv4), h2v = *(const f32x4*)(cw + 2 * NUP + cv4), hbv = *(const f32x4*)(cb + cv4);
; #pragma unroll
;             for (int ai = 0; ai < 2; ++ai) {
;                 unsigned wpk[4][2]; float rlo[4];
; #pragma unroll
;                 for (int i = 0; i < 4; ++i) {
;                     const float g0 = g0v[i], g1 = g1v[i], g2 = g2v[i], gb = gbv[i], h0 = h0v[i], h1 = h1v[i], h2 = h2v[i], hb = hbv[i];
;                     float gt[4], vl[4];
; #pragma unroll
;                     for (int m = 0; m < 4; ++m) { gt[m] = __builtin_fmaf(g1, acc[ai][0][m][n][i], gb); vl[m] = __builtin_fmaf(h1, acc[ai][1][m][n][i], hb); }
; #pragma unroll
;                     for (int m = 0; m < 4; ++m) {
;                         CONV_TAP(gt[m], acc[ai][0][m][n][i], g0, "row_shr:1"); CONV_TAP(gt[m], acc[ai][0][m][n][i], g2, "row_shl:1");
;                         CONV_TAP(vl[m], acc[ai][1][m][n][i], h0, "row_shr:1"); CONV_TAP(vl[m], acc[ai][1][m][n][i], h2, "row_shl:1");
;                         if (m > 0) { CONV_TAP(gt[m], acc[ai][0][m - 1][n][i], g0, "row_shl:15"); CONV_TAP(vl[m], acc[ai][1][m - 1][n][i], h0, "row_shl:15"); }
;                         if (m < 3) { CONV_TAP(gt[m], acc[ai][0][m + 1][n][i], g2, "row_shr:15"); CONV_TAP(vl[m], acc[ai][1][m + 1][n][i], h2, "row_shr:15"); }
;                     }
; #pragma unroll
;                     for (int m = 0; m < 4; ++m) {
;                         const float sg = gt[m] * fast_rcp(1.f + fast_exp2(-LOG2E * gt[m]));
;                         const float rv = sg * vl[m];
;                         if (i & 1) wpk[m][i >> 1] = cvtpk(rlo[m], rv); else rlo[m] = rv;
;                     }
;                     asm volatile("" ::: "memory");
;                 }
; #pragma unroll
;                 for (int m = 0; m < 4; ++m) { u32x2 w; w.x = wpk[m][0]; w.y = wpk[m][1];
;                     *(u32x2*)(ACT + (size_t)(row0 + ai * 128 + m * 16) * DFF + gcol + 4 * n) = w; }
	v_lshl_add_u64 v[148:149], v[148:149], 0, v[160:161]
	v_lshl_add_u64 v[150:151], v[150:151], 0, v[160:161]
	v_fmac_f32_dpp v19, v155, v21 row_shr:1 row_mask:0xf bank_mask:0xf bound_ctrl:0
	v_fmac_f32_dpp v27, v157, v21 row_shr:1 row_mask:0xf bank_mask:0xf bound_ctrl:0
	v_fmac_f32_dpp v9, v83, v21 row_shr:1 row_mask:0xf bank_mask:0xf bound_ctrl:0
	global_store_dwordx2 v[146:147], v[200:201], off
	global_store_dwordx2 v[148:149], v[198:199], off
	global_store_dwordx2 v[150:151], v[188:189], off
	v_fmac_f32_dpp v19, v155, v29 row_shl:1 row_mask:0xf bank_mask:0xf bound_ctrl:0
	v_fmac_f32_dpp v27, v157, v29 row_shl:1 row_mask:0xf bank_mask:0xf bound_ctrl:0
	v_fmac_f32_dpp v9, v83, v29 row_shl:1 row_mask:0xf bank_mask:0xf bound_ctrl:0
	v_add_f32_e32 v7, 1.0, v7
	v_fmac_f32_dpp v165, v117, v21 row_shr:1 row_mask:0xf bank_mask:0xf bound_ctrl:0
	v_fmac_f32_dpp v19, v117, v21 row_shl:15 row_mask:0xf bank_mask:0xf bound_ctrl:0
	v_fmac_f32_dpp v27, v155, v21 row_shl:15 row_mask:0xf bank_mask:0xf bound_ctrl:0
	v_fmac_f32_dpp v9, v157, v21 row_shl:15 row_mask:0xf bank_mask:0xf bound_ctrl:0
	v_rcp_f32_e32 v21, v7
	v_pk_mul_f32 v[4:5], v[4:5], v[12:13]
	v_fmac_f32_dpp v164, v116, v28 row_shl:1 row_mask:0xf bank_mask:0xf bound_ctrl:0
	v_fmac_f32_dpp v165, v117, v29 row_shl:1 row_mask:0xf bank_mask:0xf bound_ctrl:0
	v_pk_mul_f32 v[16:17], v[162:163], v[16:17]
	v_add_f32_e32 v11, 1.0, v11
	v_pk_mul_f32 v[4:5], v[8:9], v[4:5]
	v_cvt_pk_bf16_f32 v14, v14, v15
	v_fmac_f32_dpp v164, v154, v28 row_shr:15 row_mask:0xf bank_mask:0xf bound_ctrl:0
	v_fmac_f32_dpp v165, v155, v29 row_shr:15 row_mask:0xf bank_mask:0xf bound_ctrl:0
	v_rcp_f32_e32 v25, v11
	v_pk_mul_f32 v[16:17], v[164:165], v[16:17]
	v_cvt_pk_bf16_f32 v15, v4, v5
	v_mad_i64_i32 v[4:5], s[20:21], v102, s12, v[158:159]
	v_cvt_pk_bf16_f32 v3, v16, v17
	v_lshl_add_u64 v[80:81], v[4:5], 0, v[160:161]
	v_pk_mul_f32 v[16:17], v[22:23], v[20:21]
	global_store_dwordx2 v[80:81], v[2:3], off
	v_mad_i64_i32 v[2:3], s[20:21], v104, s12, v[158:159]
	v_fmac_f32_dpp v18, v156, v28 row_shr:15 row_mask:0xf bank_mask:0xf bound_ctrl:0
	v_fmac_f32_dpp v26, v82, v28 row_shr:15 row_mask:0xf bank_mask:0xf bound_ctrl:0
	v_fmac_f32_dpp v19, v157, v29 row_shr:15 row_mask:0xf bank_mask:0xf bound_ctrl:0
	v_fmac_f32_dpp v27, v83, v29 row_shr:15 row_mask:0xf bank_mask:0xf bound_ctrl:0
	v_lshl_add_u64 v[82:83], v[2:3], 0, v[160:161]
	v_pk_mul_f32 v[16:17], v[18:19], v[16:17]
	v_mad_i64_i32 v[2:3], s[20:21], v110, s12, v[158:159]
	v_cvt_pk_bf16_f32 v7, v16, v17
	v_pk_mul_f32 v[16:17], v[30:31], v[24:25]
	v_lshl_add_u64 v[102:103], v[2:3], 0, v[160:161]
	v_mad_i64_i32 v[2:3], s[20:21], v112, s12, v[158:159]
	v_pk_mul_f32 v[16:17], v[26:27], v[16:17]
	v_lshl_add_u64 v[104:105], v[2:3], 0, v[160:161]
	v_or_b32_e32 v2, 4, v144
	v_cvt_pk_bf16_f32 v11, v16, v17
	v_ashrrev_i32_e32 v3, 31, v2
	global_store_dwordx2 v[82:83], v[6:7], off
	global_store_dwordx2 v[102:103], v[10:11], off
	global_store_dwordx2 v[104:105], v[14:15], off
	v_lshlrev_b64 v[2:3], 2, v[2:3]
	v_lshl_add_u64 v[4:5], s[70:71], 0, v[2:3]
	ds_read_b128 v[10:13], v70 offset:16
	ds_read_b128 v[22:25], v70 offset:528
	v_lshl_add_u64 v[2:3], s[38:39], 0, v[2:3]
	ds_read_b128 v[18:21], v70 offset:1040
	s_nop 0
	ds_read_b128 v[2:5], v70 offset:1552
	ds_read_b128 v[14:17], v70 offset:2064
	ds_read_b128 v[30:33], v70 offset:2576
	ds_read_b128 v[26:29], v70 offset:3088
	ds_read_b128 v[6:9], v70 offset:3600
	s_mov_b64 s[20:21], -1
	s_waitcnt lgkmcnt(0)
	v_fma_f32 v110, v22, v126, v2
	v_fma_f32 v88, v22, v56, v2
	v_fma_f32 v111, v23, v127, v3
	v_fma_f32 v89, v23, v57, v3
	v_fmac_f32_dpp v110, v126, v10 row_shr:1 row_mask:0xf bank_mask:0xf bound_ctrl:0
	v_fma_f32 v84, v22, v54, v2
	v_fmac_f32_dpp v88, v56, v10 row_shr:1 row_mask:0xf bank_mask:0xf bound_ctrl:0
	v_fmac_f32_dpp v111, v127, v11 row_shr:1 row_mask:0xf bank_mask:0xf bound_ctrl:0
	v_fma_f32 v85, v23, v55, v3
	v_fmac_f32_dpp v89, v57, v11 row_shr:1 row_mask:0xf bank_mask:0xf bound_ctrl:0
	v_fmac_f32_dpp v110, v126, v18 row_shl:1 row_mask:0xf bank_mask:0xf bound_ctrl:0
	v_fmac_f32_dpp v84, v54, v10 row_shr:1 row_mask:0xf bank_mask:0xf bound_ctrl:0
	v_fmac_f32_dpp v88, v56, v18 row_shl:1 row_mask:0xf bank_mask:0xf bound_ctrl:0
	v_fmac_f32_dpp v111, v127, v19 row_shl:1 row_mask:0xf bank_mask:0xf bound_ctrl:0
	v_fmac_f32_dpp v85, v55, v11 row_shr:1 row_mask:0xf bank_mask:0xf bound_ctrl:0
	s_nop 0
	v_fmac_f32_dpp v89, v57, v19 row_shl:1 row_mask:0xf bank_mask:0xf bound_ctrl:0
	v_fmac_f32_dpp v110, v54, v18 row_shr:15 row_mask:0xf bank_mask:0xf bound_ctrl:0
	v_fmac_f32_dpp v84, v54, v18 row_shl:1 row_mask:0xf bank_mask:0xf bound_ctrl:0
	v_fmac_f32_dpp v88, v54, v10 row_shl:15 row_mask:0xf bank_mask:0xf bound_ctrl:0
	v_fmac_f32_dpp v111, v55, v19 row_shr:15 row_mask:0xf bank_mask:0xf bound_ctrl:0
	v_fmac_f32_dpp v85, v55, v19 row_shl:1 row_mask:0xf bank_mask:0xf bound_ctrl:0
	s_nop 0
	v_fmac_f32_dpp v89, v55, v11 row_shl:15 row_mask:0xf bank_mask:0xf bound_ctrl:0
	v_mul_f32_e32 v54, 0xbfb8aa3b, v110
	v_mul_f32_e32 v55, 0xbfb8aa3b, v111
	v_exp_f32_e32 v54, v54
	v_exp_f32_e32 v55, v55
	v_fma_f32 v112, v30, v128, v6
	v_fma_f32 v113, v31, v129, v7
	v_add_f32_e32 v54, 1.0, v54
	v_add_f32_e32 v55, 1.0, v55
	v_rcp_f32_e32 v54, v54
	v_rcp_f32_e32 v55, v55
	v_fmac_f32_dpp v112, v128, v14 row_shr:1 row_mask:0xf bank_mask:0xf bound_ctrl:0
	v_fmac_f32_dpp v113, v129, v15 row_shr:1 row_mask:0xf bank_mask:0xf bound_ctrl:0
	v_fmac_f32_dpp v85, v127, v11 row_shl:15 row_mask:0xf bank_mask:0xf bound_ctrl:0
	v_fma_f32 v73, v23, v107, v3
	v_fmac_f32_dpp v112, v128, v26 row_shl:1 row_mask:0xf bank_mask:0xf bound_ctrl:0
; __device__ __forceinline__ unsigned cvtpk(float lo, float hi) { f32x2 v = {lo, hi}; bf16x2_t b = __builtin_convertvector(v, bf16x2_t); return __builtin_bit_cast(unsigned, b); }
; __device__ __forceinline__ float fast_exp2(float x) { return __builtin_amdgcn_exp2f(x); }
; __device__ __forceinline__ float fast_rcp(float x) { return __builtin_amdgcn_rcpf(x); }
; #define CONV_TAP(t, u, g, ctl) asm("v_fmac_f32_dpp %0, %1, %2 " ctl " row_mask:0xf bank_mask:0xf bound_ctrl:0" : "+v"(t) : "v"(u), "v"(g))
;     __device__ __forceinline__ void operator()(AccRef acc, const Unit& u, int wr, int wc, int fr, int fq) const {
;     ...
;                 for (int i = 0; i < 4; ++i) {
;                     const float g0 = g0v[i], g1 = g1v[i], g2 = g2v[i], gb = gbv[i], h0 = h0v[i], h1 = h1v[i], h2 = h2v[i], hb = hbv[i];
;                     float gt[4], vl[4];
; #pragma unroll
;                     for (int m = 0; m < 4; ++m) { gt[m] = __builtin_fmaf(g1, acc[ai][0][m][n][i], gb); vl[m] = __builtin_fmaf(h1, acc[ai][1][m][n][i], hb); }
; #pragma unroll
;                     for (int m = 0; m < 4; ++m) {
;                         CONV_TAP(gt[m], acc[ai][0][m][n][i], g0, "row_shr:1"); CONV_TAP(gt[m], acc[ai][0][m][n][i], g2, "row_shl:1");
;                         CONV_TAP(vl[m], acc[ai][1][m][n][i], h0, "row_shr:1"); CONV_TAP(vl[m], acc[ai][1][m][n][i], h2, "row_shl:1");
;                         if (m > 0) { CONV_TAP(gt[m], acc[ai][0][m - 1][n][i], g0, "row_shl:15"); CONV_TAP(vl[m], acc[ai][1][m - 1][n][i], h0, "row_shl:15"); }
;                         if (m < 3) { CONV_TAP(gt[m], acc[ai][0][m + 1][n][i], g2, "row_shr:15"); CONV_TAP(vl[m], acc[ai][1][m + 1][n][i], h2, "row_shr:15"); }
;                     }
; #pragma unroll
;                     for (int m = 0; m < 4; ++m) {
;                         const float sg = gt[m] * fast_rcp(1.f + fast_exp2(-LOG2E * gt[m]));
;                         const float rv = sg * vl[m];
;                         if (i & 1) wpk[m][i >> 1] = cvtpk(rlo[m], rv); else rlo[m] = rv;
;                     }
;                     asm volatile("" ::: "memory");
	v_fmac_f32_dpp v113, v129, v27 row_shl:1 row_mask:0xf bank_mask:0xf bound_ctrl:0
	v_pk_mul_f32 v[54:55], v[110:111], v[54:55]
	v_fmac_f32_dpp v112, v62, v26 row_shr:15 row_mask:0xf bank_mask:0xf bound_ctrl:0
	v_fmac_f32_dpp v113, v63, v27 row_shr:15 row_mask:0xf bank_mask:0xf bound_ctrl:0
	v_fmac_f32_dpp v85, v57, v19 row_shr:15 row_mask:0xf bank_mask:0xf bound_ctrl:0
	v_fmac_f32_dpp v73, v107, v11 row_shr:1 row_mask:0xf bank_mask:0xf bound_ctrl:0
	v_fmac_f32_dpp v89, v107, v19 row_shr:15 row_mask:0xf bank_mask:0xf bound_ctrl:0
	v_fma_f32 v78, v30, v62, v6
	v_pk_mul_f32 v[54:55], v[112:113], v[54:55]
	v_fmac_f32_dpp v73, v107, v19 row_shl:1 row_mask:0xf bank_mask:0xf bound_ctrl:0
	v_fma_f32 v72, v22, v106, v2
	v_cvt_pk_bf16_f32 v54, v54, v55
	v_mul_f32_e32 v55, 0xbfb8aa3b, v85
	v_exp_f32_e32 v55, v55
	v_fmac_f32_dpp v73, v57, v11 row_shl:15 row_mask:0xf bank_mask:0xf bound_ctrl:0
	v_fmac_f32_dpp v78, v62, v14 row_shr:1 row_mask:0xf bank_mask:0xf bound_ctrl:0
	v_fma_f32 v86, v30, v64, v6
	v_add_f32_e32 v55, 1.0, v55
	v_rcp_f32_e32 v57, v55
	v_mul_f32_e32 v55, 0xbfb8aa3b, v89
	v_exp_f32_e32 v55, v55
	v_fma_f32 v70, v30, v98, v6
	v_fmac_f32_dpp v72, v106, v10 row_shr:1 row_mask:0xf bank_mask:0xf bound_ctrl:0
	v_fma_f32 v87, v31, v65, v7
	v_fmac_f32_dpp v78, v62, v26 row_shl:1 row_mask:0xf bank_mask:0xf bound_ctrl:0
	v_fmac_f32_dpp v84, v126, v10 row_shl:15 row_mask:0xf bank_mask:0xf bound_ctrl:0
	v_fmac_f32_dpp v86, v64, v14 row_shr:1 row_mask:0xf bank_mask:0xf bound_ctrl:0
	v_fmac_f32_dpp v72, v106, v18 row_shl:1 row_mask:0xf bank_mask:0xf bound_ctrl:0
	v_fmac_f32_dpp v70, v98, v14 row_shr:1 row_mask:0xf bank_mask:0xf bound_ctrl:0
	v_fma_f32 v79, v31, v63, v7
	v_fmac_f32_dpp v87, v65, v15 row_shr:1 row_mask:0xf bank_mask:0xf bound_ctrl:0
	v_fmac_f32_dpp v78, v128, v14 row_shl:15 row_mask:0xf bank_mask:0xf bound_ctrl:0
	v_fmac_f32_dpp v84, v56, v18 row_shr:15 row_mask:0xf bank_mask:0xf bound_ctrl:0
	v_fmac_f32_dpp v86, v64, v26 row_shl:1 row_mask:0xf bank_mask:0xf bound_ctrl:0
	v_fmac_f32_dpp v70, v98, v26 row_shl:1 row_mask:0xf bank_mask:0xf bound_ctrl:0
	v_fmac_f32_dpp v72, v56, v10 row_shl:15 row_mask:0xf bank_mask:0xf bound_ctrl:0
	v_fmac_f32_dpp v79, v63, v15 row_shr:1 row_mask:0xf bank_mask:0xf bound_ctrl:0
	s_nop 0
	v_fmac_f32_dpp v87, v65, v27 row_shl:1 row_mask:0xf bank_mask:0xf bound_ctrl:0
	v_mul_f32_e32 v56, 0xbfb8aa3b, v84
	v_add_f32_e32 v55, 1.0, v55
	v_fmac_f32_dpp v78, v64, v26 row_shr:15 row_mask:0xf bank_mask:0xf bound_ctrl:0
	v_fmac_f32_dpp v86, v62, v14 row_shl:15 row_mask:0xf bank_mask:0xf bound_ctrl:0
	v_fmac_f32_dpp v88, v106, v18 row_shr:15 row_mask:0xf bank_mask:0xf bound_ctrl:0
	v_fmac_f32_dpp v70, v64, v14 row_shl:15 row_mask:0xf bank_mask:0xf bound_ctrl:0
	v_exp_f32_e32 v56, v56
	v_mul_f32_e32 v62, 0xbfb8aa3b, v88
	v_mul_f32_e32 v64, 0xbfb8aa3b, v72
	v_fmac_f32_dpp v79, v63, v27 row_shl:1 row_mask:0xf bank_mask:0xf bound_ctrl:0
	v_fmac_f32_dpp v87, v63, v15 row_shl:15 row_mask:0xf bank_mask:0xf bound_ctrl:0
	v_rcp_f32_e32 v63, v55
	v_mul_f32_e32 v55, 0xbfb8aa3b, v73
	v_exp_f32_e32 v62, v62
	v_exp_f32_e32 v64, v64
	v_exp_f32_e32 v55, v55
	v_fma_f32 v71, v31, v99, v7
	v_add_f32_e32 v56, 1.0, v56
	v_fmac_f32_dpp v71, v99, v15 row_shr:1 row_mask:0xf bank_mask:0xf bound_ctrl:0
	v_rcp_f32_e32 v56, v56
	v_add_f32_e32 v62, 1.0, v62
	v_add_f32_e32 v64, 1.0, v64
	v_fmac_f32_dpp v79, v129, v15 row_shl:15 row_mask:0xf bank_mask:0xf bound_ctrl:0
	v_fmac_f32_dpp v71, v99, v27 row_shl:1 row_mask:0xf bank_mask:0xf bound_ctrl:0
	v_add_f32_e32 v55, 1.0, v55
	v_rcp_f32_e32 v62, v62
	v_rcp_f32_e32 v64, v64
	v_fmac_f32_dpp v79, v65, v27 row_shr:15 row_mask:0xf bank_mask:0xf bound_ctrl:0
	v_fmac_f32_dpp v71, v65, v15 row_shl:15 row_mask:0xf bank_mask:0xf bound_ctrl:0
	v_rcp_f32_e32 v65, v55
	v_pk_mul_f32 v[56:57], v[84:85], v[56:57]
	v_pk_mul_f32 v[62:63], v[88:89], v[62:63]
	v_pk_mul_f32 v[56:57], v[78:79], v[56:57]
	v_pk_mul_f32 v[64:65], v[72:73], v[64:65]
	v_fma_f32 v88, v32, v124, v8
	v_fma_f32 v78, v32, v46, v8
	v_fma_f32 v89, v33, v125, v9
	v_fma_f32 v79, v33, v47, v9
	v_pk_mul_f32 v[64:65], v[70:71], v[64:65]
	v_fmac_f32_dpp v88, v124, v16 row_shr:1 row_mask:0xf bank_mask:0xf bound_ctrl:0
	v_fma_f32 v70, v32, v48, v8
	v_fmac_f32_dpp v78, v46, v16 row_shr:1 row_mask:0xf bank_mask:0xf bound_ctrl:0
	v_fmac_f32_dpp v89, v125, v17 row_shr:1 row_mask:0xf bank_mask:0xf bound_ctrl:0
	v_fma_f32 v71, v33, v49, v9
	v_fmac_f32_dpp v79, v47, v17 row_shr:1 row_mask:0xf bank_mask:0xf bound_ctrl:0
	v_fmac_f32_dpp v86, v98, v26 row_shr:15 row_mask:0xf bank_mask:0xf bound_ctrl:0
	v_fmac_f32_dpp v87, v99, v27 row_shr:15 row_mask:0xf bank_mask:0xf bound_ctrl:0
	v_fmac_f32_dpp v88, v124, v28 row_shl:1 row_mask:0xf bank_mask:0xf bound_ctrl:0
	v_fma_f32 v72, v24, v38, v4
	v_fmac_f32_dpp v70, v48, v16 row_shr:1 row_mask:0xf bank_mask:0xf bound_ctrl:0
	v_fmac_f32_dpp v78, v46, v28 row_shl:1 row_mask:0xf bank_mask:0xf bound_ctrl:0
	v_fmac_f32_dpp v89, v125, v29 row_shl:1 row_mask:0xf bank_mask:0xf bound_ctrl:0
	v_fma_f32 v73, v25, v39, v5
	v_fmac_f32_dpp v71, v49, v17 row_shr:1 row_mask:0xf bank_mask:0xf bound_ctrl:0
	v_fmac_f32_dpp v79, v47, v29 row_shl:1 row_mask:0xf bank_mask:0xf bound_ctrl:0
	v_pk_mul_f32 v[62:63], v[86:87], v[62:63]
	v_fma_f32 v86, v24, v122, v4
	v_fmac_f32_dpp v88, v48, v28 row_shr:15 row_mask:0xf bank_mask:0xf bound_ctrl:0
	v_fmac_f32_dpp v72, v38, v12 row_shr:1 row_mask:0xf bank_mask:0xf bound_ctrl:0
	v_fmac_f32_dpp v70, v48, v28 row_shl:1 row_mask:0xf bank_mask:0xf bound_ctrl:0
	v_fmac_f32_dpp v78, v48, v16 row_shl:15 row_mask:0xf bank_mask:0xf bound_ctrl:0
	v_fma_f32 v48, v24, v108, v4
	v_fma_f32 v87, v25, v123, v5
; __device__ __forceinline__ unsigned cvtpk(float lo, float hi) { f32x2 v = {lo, hi}; bf16x2_t b = __builtin_convertvector(v, bf16x2_t); return __builtin_bit_cast(unsigned, b); }
; __device__ __forceinline__ float fast_exp2(float x) { return __builtin_amdgcn_exp2f(x); }
; __device__ __forceinline__ float fast_rcp(float x) { return __builtin_amdgcn_rcpf(x); }
; #define CONV_TAP(t, u, g, ctl) asm("v_fmac_f32_dpp %0, %1, %2 " ctl " row_mask:0xf bank_mask:0xf bound_ctrl:0" : "+v"(t) : "v"(u), "v"(g))
;     __device__ __forceinline__ void operator()(AccRef acc, const Unit& u, int wr, int wc, int fr, int fq) const {
;     ...
;                 for (int i = 0; i < 4; ++i) {
;                     const float g0 = g0v[i], g1 = g1v[i], g2 = g2v[i], gb = gbv[i], h0 = h0v[i], h1 = h1v[i], h2 = h2v[i], hb = hbv[i];
;                     float gt[4], vl[4];
; #pragma unroll
;                     for (int m = 0; m < 4; ++m) { gt[m] = __builtin_fmaf(g1, acc[ai][0][m][n][i], gb); vl[m] = __builtin_fmaf(h1, acc[ai][1][m][n][i], hb); }
; #pragma unroll
;                     for (int m = 0; m < 4; ++m) {
;                         CONV_TAP(gt[m], acc[ai][0][m][n][i], g0, "row_shr:1"); CONV_TAP(gt[m], acc[ai][0][m][n][i], g2, "row_shl:1");
;                         CONV_TAP(vl[m], acc[ai][1][m][n][i], h0, "row_shr:1"); CONV_TAP(vl[m], acc[ai][1][m][n][i], h2, "row_shl:1");
;                         if (m > 0) { CONV_TAP(gt[m], acc[ai][0][m - 1][n][i], g0, "row_shl:15"); CONV_TAP(vl[m], acc[ai][1][m - 1][n][i], h0, "row_shl:15"); }
;                         if (m < 3) { CONV_TAP(gt[m], acc[ai][0][m + 1][n][i], g2, "row_shr:15"); CONV_TAP(vl[m], acc[ai][1][m + 1][n][i], h2, "row_shr:15"); }
;                     }
; #pragma unroll
;                     for (int m = 0; m < 4; ++m) {
;                         const float sg = gt[m] * fast_rcp(1.f + fast_exp2(-LOG2E * gt[m]));
;                         const float rv = sg * vl[m];
;                         if (i & 1) wpk[m][i >> 1] = cvtpk(rlo[m], rv); else rlo[m] = rv;
;                     }
;                     asm volatile("" ::: "memory");
;                 }
; #pragma unroll
;                 for (int m = 0; m < 4; ++m) { u32x2 w; w.x = wpk[m][0]; w.y = wpk[m][1];
;                     *(u32x2*)(ACT + (size_t)(row0 + ai * 128 + m * 16) * DFF + gcol + 4 * n) = w; }
;                 asm volatile("" ::: "memory");
	v_fmac_f32_dpp v89, v49, v29 row_shr:15 row_mask:0xf bank_mask:0xf bound_ctrl:0
	v_fmac_f32_dpp v73, v39, v13 row_shr:1 row_mask:0xf bank_mask:0xf bound_ctrl:0
	v_fmac_f32_dpp v71, v49, v29 row_shl:1 row_mask:0xf bank_mask:0xf bound_ctrl:0
	v_fmac_f32_dpp v79, v49, v17 row_shl:15 row_mask:0xf bank_mask:0xf bound_ctrl:0
	v_fma_f32 v49, v25, v109, v5
	v_fmac_f32_dpp v86, v122, v12 row_shr:1 row_mask:0xf bank_mask:0xf bound_ctrl:0
	v_fmac_f32_dpp v72, v38, v20 row_shl:1 row_mask:0xf bank_mask:0xf bound_ctrl:0
	v_fma_f32 v84, v24, v40, v4
	v_fmac_f32_dpp v48, v108, v12 row_shr:1 row_mask:0xf bank_mask:0xf bound_ctrl:0
	v_fmac_f32_dpp v87, v123, v13 row_shr:1 row_mask:0xf bank_mask:0xf bound_ctrl:0
	v_fmac_f32_dpp v73, v39, v21 row_shl:1 row_mask:0xf bank_mask:0xf bound_ctrl:0
	v_fma_f32 v85, v25, v41, v5
	v_fmac_f32_dpp v49, v109, v13 row_shr:1 row_mask:0xf bank_mask:0xf bound_ctrl:0
	v_fmac_f32_dpp v86, v122, v20 row_shl:1 row_mask:0xf bank_mask:0xf bound_ctrl:0
	v_fmac_f32_dpp v72, v122, v12 row_shl:15 row_mask:0xf bank_mask:0xf bound_ctrl:0
	v_fmac_f32_dpp v84, v40, v12 row_shr:1 row_mask:0xf bank_mask:0xf bound_ctrl:0
	v_fmac_f32_dpp v48, v108, v20 row_shl:1 row_mask:0xf bank_mask:0xf bound_ctrl:0
	v_fmac_f32_dpp v87, v123, v21 row_shl:1 row_mask:0xf bank_mask:0xf bound_ctrl:0
	v_fmac_f32_dpp v73, v123, v13 row_shl:15 row_mask:0xf bank_mask:0xf bound_ctrl:0
	v_fmac_f32_dpp v85, v41, v13 row_shr:1 row_mask:0xf bank_mask:0xf bound_ctrl:0
	s_nop 0
	v_fmac_f32_dpp v49, v109, v21 row_shl:1 row_mask:0xf bank_mask:0xf bound_ctrl:0
	v_fmac_f32_dpp v86, v38, v20 row_shr:15 row_mask:0xf bank_mask:0xf bound_ctrl:0
	v_fmac_f32_dpp v72, v40, v20 row_shr:15 row_mask:0xf bank_mask:0xf bound_ctrl:0
	v_fmac_f32_dpp v84, v40, v20 row_shl:1 row_mask:0xf bank_mask:0xf bound_ctrl:0
	v_fmac_f32_dpp v48, v40, v12 row_shl:15 row_mask:0xf bank_mask:0xf bound_ctrl:0
	v_fmac_f32_dpp v87, v39, v21 row_shr:15 row_mask:0xf bank_mask:0xf bound_ctrl:0
	v_fmac_f32_dpp v73, v41, v21 row_shr:15 row_mask:0xf bank_mask:0xf bound_ctrl:0
	s_nop 0
	v_mul_f32_e32 v40, 0xbfb8aa3b, v86
	v_fmac_f32_dpp v85, v41, v21 row_shl:1 row_mask:0xf bank_mask:0xf bound_ctrl:0
	v_fmac_f32_dpp v49, v41, v13 row_shl:15 row_mask:0xf bank_mask:0xf bound_ctrl:0
	v_mul_f32_e32 v41, 0xbfb8aa3b, v87
	v_exp_f32_e32 v40, v40
	v_exp_f32_e32 v41, v41
	v_fmac_f32_dpp v84, v38, v12 row_shl:15 row_mask:0xf bank_mask:0xf bound_ctrl:0
	v_fma_f32 v38, v32, v100, v8
	v_fmac_f32_dpp v85, v39, v13 row_shl:15 row_mask:0xf bank_mask:0xf bound_ctrl:0
	v_fma_f32 v39, v33, v101, v9
	v_fmac_f32_dpp v38, v100, v16 row_shr:1 row_mask:0xf bank_mask:0xf bound_ctrl:0
	v_fmac_f32_dpp v39, v101, v17 row_shr:1 row_mask:0xf bank_mask:0xf bound_ctrl:0
	v_fmac_f32_dpp v70, v124, v16 row_shl:15 row_mask:0xf bank_mask:0xf bound_ctrl:0
	v_add_f32_e32 v40, 1.0, v40
	v_fmac_f32_dpp v38, v100, v28 row_shl:1 row_mask:0xf bank_mask:0xf bound_ctrl:0
	v_fmac_f32_dpp v71, v125, v17 row_shl:15 row_mask:0xf bank_mask:0xf bound_ctrl:0
	v_fmac_f32_dpp v39, v101, v29 row_shl:1 row_mask:0xf bank_mask:0xf bound_ctrl:0
	v_add_f32_e32 v41, 1.0, v41
	v_fmac_f32_dpp v70, v46, v28 row_shr:15 row_mask:0xf bank_mask:0xf bound_ctrl:0
	v_fmac_f32_dpp v38, v46, v16 row_shl:15 row_mask:0xf bank_mask:0xf bound_ctrl:0
	v_rcp_f32_e32 v46, v40
	v_mul_f32_e32 v40, 0xbfb8aa3b, v72
	v_fmac_f32_dpp v71, v47, v29 row_shr:15 row_mask:0xf bank_mask:0xf bound_ctrl:0
	v_fmac_f32_dpp v39, v47, v17 row_shl:15 row_mask:0xf bank_mask:0xf bound_ctrl:0
	v_rcp_f32_e32 v47, v41
	v_mul_f32_e32 v41, 0xbfb8aa3b, v73
	v_exp_f32_e32 v40, v40
	v_exp_f32_e32 v41, v41
	v_fmac_f32_dpp v84, v108, v20 row_shr:15 row_mask:0xf bank_mask:0xf bound_ctrl:0
	v_fmac_f32_dpp v85, v109, v21 row_shr:15 row_mask:0xf bank_mask:0xf bound_ctrl:0
	v_add_f32_e32 v40, 1.0, v40
	v_add_f32_e32 v41, 1.0, v41
	v_rcp_f32_e32 v98, v40
	v_mul_f32_e32 v40, 0xbfb8aa3b, v84
	v_rcp_f32_e32 v99, v41
	v_mul_f32_e32 v41, 0xbfb8aa3b, v85
	v_exp_f32_e32 v40, v40
	v_exp_f32_e32 v41, v41
	v_fmac_f32_dpp v78, v100, v28 row_shr:15 row_mask:0xf bank_mask:0xf bound_ctrl:0
	v_fmac_f32_dpp v79, v101, v29 row_shr:15 row_mask:0xf bank_mask:0xf bound_ctrl:0
	v_add_f32_e32 v40, 1.0, v40
	v_add_f32_e32 v41, 1.0, v41
	v_rcp_f32_e32 v100, v40
	v_mul_f32_e32 v40, 0xbfb8aa3b, v48
	v_rcp_f32_e32 v101, v41
	v_mul_f32_e32 v41, 0xbfb8aa3b, v49
	v_exp_f32_e32 v40, v40
	v_exp_f32_e32 v41, v41
	v_pk_mul_f32 v[46:47], v[86:87], v[46:47]
	v_cvt_pk_bf16_f32 v56, v56, v57
	v_add_f32_e32 v40, 1.0, v40
	v_add_f32_e32 v41, 1.0, v41
	v_rcp_f32_e32 v40, v40
	v_rcp_f32_e32 v41, v41
	v_pk_mul_f32 v[46:47], v[88:89], v[46:47]
	v_cvt_pk_bf16_f32 v62, v62, v63
	v_cvt_pk_bf16_f32 v55, v46, v47
	v_pk_mul_f32 v[46:47], v[72:73], v[98:99]
	v_pk_mul_f32 v[40:41], v[48:49], v[40:41]
	v_pk_mul_f32 v[46:47], v[70:71], v[46:47]
	v_pk_mul_f32 v[38:39], v[38:39], v[40:41]
	v_cvt_pk_bf16_f32 v57, v46, v47
	v_pk_mul_f32 v[46:47], v[84:85], v[100:101]
	v_cvt_pk_bf16_f32 v64, v64, v65
	v_pk_mul_f32 v[46:47], v[78:79], v[46:47]
	v_cvt_pk_bf16_f32 v65, v38, v39
	v_cvt_pk_bf16_f32 v63, v46, v47
	global_store_dwordx2 v[146:147], v[54:55], off offset:8
	global_store_dwordx2 v[148:149], v[56:57], off offset:8
	global_store_dwordx2 v[150:151], v[62:63], off offset:8
	global_store_dwordx2 v[152:153], v[64:65], off offset:8
	v_fma_f32 v40, v22, v94, v2
	v_fma_f32 v48, v22, v58, v2
	v_fma_f32 v56, v22, v42, v2
	v_fma_f32 v2, v22, v74, v2
	v_fma_f32 v41, v23, v95, v3
	v_fma_f32 v49, v23, v59, v3
	v_fma_f32 v57, v23, v43, v3
	v_fma_f32 v3, v23, v75, v3
	v_fmac_f32_dpp v48, v58, v10 row_shr:1 row_mask:0xf bank_mask:0xf bound_ctrl:0
	v_fmac_f32_dpp v56, v42, v10 row_shr:1 row_mask:0xf bank_mask:0xf bound_ctrl:0
; __device__ __forceinline__ unsigned cvtpk(float lo, float hi) { f32x2 v = {lo, hi}; bf16x2_t b = __builtin_convertvector(v, bf16x2_t); return __builtin_bit_cast(unsigned, b); }
; __device__ __forceinline__ float fast_exp2(float x) { return __builtin_amdgcn_exp2f(x); }
; __device__ __forceinline__ float fast_rcp(float x) { return __builtin_amdgcn_rcpf(x); }
; #define CONV_TAP(t, u, g, ctl) asm("v_fmac_f32_dpp %0, %1, %2 " ctl " row_mask:0xf bank_mask:0xf bound_ctrl:0" : "+v"(t) : "v"(u), "v"(g))
;     __device__ __forceinline__ void operator()(AccRef acc, const Unit& u, int wr, int wc, int fr, int fq) const {
;     ...
;                 for (int i = 0; i < 4; ++i) {
;                     const float g0 = g0v[i], g1 = g1v[i], g2 = g2v[i], gb = gbv[i], h0 = h0v[i], h1 = h1v[i], h2 = h2v[i], hb = hbv[i];
;                     float gt[4], vl[4];
; #pragma unroll
;                     for (int m = 0; m < 4; ++m) { gt[m] = __builtin_fmaf(g1, acc[ai][0][m][n][i], gb); vl[m] = __builtin_fmaf(h1, acc[ai][1][m][n][i], hb); }
; #pragma unroll
;                     for (int m = 0; m < 4; ++m) {
;                         CONV_TAP(gt[m], acc[ai][0][m][n][i], g0, "row_shr:1"); CONV_TAP(gt[m], acc[ai][0][m][n][i], g2, "row_shl:1");
;                         CONV_TAP(vl[m], acc[ai][1][m][n][i], h0, "row_shr:1"); CONV_TAP(vl[m], acc[ai][1][m][n][i], h2, "row_shl:1");
;                         if (m > 0) { CONV_TAP(gt[m], acc[ai][0][m - 1][n][i], g0, "row_shl:15"); CONV_TAP(vl[m], acc[ai][1][m - 1][n][i], h0, "row_shl:15"); }
;                         if (m < 3) { CONV_TAP(gt[m], acc[ai][0][m + 1][n][i], g2, "row_shr:15"); CONV_TAP(vl[m], acc[ai][1][m + 1][n][i], h2, "row_shr:15"); }
;                     }
; #pragma unroll
;                     for (int m = 0; m < 4; ++m) {
;                         const float sg = gt[m] * fast_rcp(1.f + fast_exp2(-LOG2E * gt[m]));
;                         const float rv = sg * vl[m];
;                         if (i & 1) wpk[m][i >> 1] = cvtpk(rlo[m], rv); else rlo[m] = rv;
;                     }
;                     asm volatile("" ::: "memory");
	v_fmac_f32_dpp v2, v74, v10 row_shr:1 row_mask:0xf bank_mask:0xf bound_ctrl:0
	v_fmac_f32_dpp v49, v59, v11 row_shr:1 row_mask:0xf bank_mask:0xf bound_ctrl:0
	v_fmac_f32_dpp v57, v43, v11 row_shr:1 row_mask:0xf bank_mask:0xf bound_ctrl:0
	v_fmac_f32_dpp v3, v75, v11 row_shr:1 row_mask:0xf bank_mask:0xf bound_ctrl:0
	s_nop 0
	v_fmac_f32_dpp v48, v58, v18 row_shl:1 row_mask:0xf bank_mask:0xf bound_ctrl:0
	v_fmac_f32_dpp v56, v42, v18 row_shl:1 row_mask:0xf bank_mask:0xf bound_ctrl:0
	v_fmac_f32_dpp v2, v74, v18 row_shl:1 row_mask:0xf bank_mask:0xf bound_ctrl:0
	v_fmac_f32_dpp v49, v59, v19 row_shl:1 row_mask:0xf bank_mask:0xf bound_ctrl:0
	v_fmac_f32_dpp v57, v43, v19 row_shl:1 row_mask:0xf bank_mask:0xf bound_ctrl:0
	v_fmac_f32_dpp v3, v75, v19 row_shl:1 row_mask:0xf bank_mask:0xf bound_ctrl:0
	v_fma_f32 v38, v30, v96, v6
	v_fmac_f32_dpp v40, v94, v10 row_shr:1 row_mask:0xf bank_mask:0xf bound_ctrl:0
	v_fma_f32 v46, v30, v50, v6
	v_fmac_f32_dpp v48, v94, v10 row_shl:15 row_mask:0xf bank_mask:0xf bound_ctrl:0
	v_fma_f32 v54, v30, v34, v6
	v_fmac_f32_dpp v56, v58, v10 row_shl:15 row_mask:0xf bank_mask:0xf bound_ctrl:0
	v_fma_f32 v6, v30, v66, v6
	v_fmac_f32_dpp v2, v42, v10 row_shl:15 row_mask:0xf bank_mask:0xf bound_ctrl:0
	v_fma_f32 v39, v31, v97, v7
	v_fmac_f32_dpp v41, v95, v11 row_shr:1 row_mask:0xf bank_mask:0xf bound_ctrl:0
	v_fma_f32 v47, v31, v51, v7
	v_fmac_f32_dpp v49, v95, v11 row_shl:15 row_mask:0xf bank_mask:0xf bound_ctrl:0
	v_fma_f32 v55, v31, v35, v7
	v_fmac_f32_dpp v57, v59, v11 row_shl:15 row_mask:0xf bank_mask:0xf bound_ctrl:0
	v_fma_f32 v7, v31, v67, v7
	v_fmac_f32_dpp v3, v43, v11 row_shl:15 row_mask:0xf bank_mask:0xf bound_ctrl:0
	v_fma_f32 v10, v24, v92, v4
	v_fma_f32 v22, v24, v60, v4
	v_fma_f32 v30, v24, v44, v4
	v_fma_f32 v4, v24, v76, v4
	v_fma_f32 v11, v25, v93, v5
	v_fma_f32 v23, v25, v61, v5
	v_fma_f32 v31, v25, v45, v5
	v_fmac_f32_e32 v5, v25, v77
	v_fmac_f32_dpp v22, v60, v12 row_shr:1 row_mask:0xf bank_mask:0xf bound_ctrl:0
	v_fmac_f32_dpp v30, v44, v12 row_shr:1 row_mask:0xf bank_mask:0xf bound_ctrl:0
	v_fmac_f32_dpp v4, v76, v12 row_shr:1 row_mask:0xf bank_mask:0xf bound_ctrl:0
	v_fmac_f32_dpp v23, v61, v13 row_shr:1 row_mask:0xf bank_mask:0xf bound_ctrl:0
	v_fmac_f32_dpp v31, v45, v13 row_shr:1 row_mask:0xf bank_mask:0xf bound_ctrl:0
	v_fmac_f32_dpp v5, v77, v13 row_shr:1 row_mask:0xf bank_mask:0xf bound_ctrl:0
	s_nop 0
	v_fmac_f32_dpp v22, v60, v20 row_shl:1 row_mask:0xf bank_mask:0xf bound_ctrl:0
	v_fmac_f32_dpp v30, v44, v20 row_shl:1 row_mask:0xf bank_mask:0xf bound_ctrl:0
	v_fmac_f32_dpp v4, v76, v20 row_shl:1 row_mask:0xf bank_mask:0xf bound_ctrl:0
	v_fmac_f32_dpp v23, v61, v21 row_shl:1 row_mask:0xf bank_mask:0xf bound_ctrl:0
	v_fmac_f32_dpp v31, v45, v21 row_shl:1 row_mask:0xf bank_mask:0xf bound_ctrl:0
	v_fmac_f32_dpp v5, v77, v21 row_shl:1 row_mask:0xf bank_mask:0xf bound_ctrl:0
	v_fmac_f32_dpp v10, v92, v12 row_shr:1 row_mask:0xf bank_mask:0xf bound_ctrl:0
	s_nop 0
	v_fmac_f32_dpp v22, v92, v12 row_shl:15 row_mask:0xf bank_mask:0xf bound_ctrl:0
	v_fmac_f32_dpp v30, v60, v12 row_shl:15 row_mask:0xf bank_mask:0xf bound_ctrl:0
	v_fmac_f32_dpp v4, v44, v12 row_shl:15 row_mask:0xf bank_mask:0xf bound_ctrl:0
	v_fmac_f32_dpp v11, v93, v13 row_shr:1 row_mask:0xf bank_mask:0xf bound_ctrl:0
	v_fmac_f32_dpp v23, v93, v13 row_shl:15 row_mask:0xf bank_mask:0xf bound_ctrl:0
	v_fmac_f32_dpp v31, v61, v13 row_shl:15 row_mask:0xf bank_mask:0xf bound_ctrl:0
	v_fmac_f32_dpp v5, v45, v13 row_shl:15 row_mask:0xf bank_mask:0xf bound_ctrl:0
	v_fmac_f32_dpp v46, v50, v14 row_shr:1 row_mask:0xf bank_mask:0xf bound_ctrl:0
	s_nop 0
	v_mul_f32_e32 v12, 0xbfb8aa3b, v4
	v_mul_f32_e32 v13, 0xbfb8aa3b, v5
	v_exp_f32_e32 v12, v12
	v_exp_f32_e32 v13, v13
	v_fmac_f32_dpp v54, v34, v14 row_shr:1 row_mask:0xf bank_mask:0xf bound_ctrl:0
	v_fmac_f32_dpp v47, v51, v15 row_shr:1 row_mask:0xf bank_mask:0xf bound_ctrl:0
	v_fmac_f32_dpp v55, v35, v15 row_shr:1 row_mask:0xf bank_mask:0xf bound_ctrl:0
	v_add_f32_e32 v12, 1.0, v12
	v_add_f32_e32 v13, 1.0, v13
	v_fmac_f32_dpp v38, v96, v14 row_shr:1 row_mask:0xf bank_mask:0xf bound_ctrl:0
	v_fmac_f32_dpp v46, v50, v26 row_shl:1 row_mask:0xf bank_mask:0xf bound_ctrl:0
	v_fmac_f32_dpp v54, v34, v26 row_shl:1 row_mask:0xf bank_mask:0xf bound_ctrl:0
	v_fmac_f32_dpp v6, v66, v14 row_shr:1 row_mask:0xf bank_mask:0xf bound_ctrl:0
	v_fmac_f32_dpp v39, v97, v15 row_shr:1 row_mask:0xf bank_mask:0xf bound_ctrl:0
	v_fmac_f32_dpp v47, v51, v27 row_shl:1 row_mask:0xf bank_mask:0xf bound_ctrl:0
	v_fmac_f32_dpp v55, v35, v27 row_shl:1 row_mask:0xf bank_mask:0xf bound_ctrl:0
	v_fmac_f32_dpp v7, v67, v15 row_shr:1 row_mask:0xf bank_mask:0xf bound_ctrl:0
	v_rcp_f32_e32 v12, v12
	v_rcp_f32_e32 v13, v13
	v_fmac_f32_dpp v40, v94, v18 row_shl:1 row_mask:0xf bank_mask:0xf bound_ctrl:0
	v_fmac_f32_dpp v38, v96, v26 row_shl:1 row_mask:0xf bank_mask:0xf bound_ctrl:0
	v_fmac_f32_dpp v46, v96, v14 row_shl:15 row_mask:0xf bank_mask:0xf bound_ctrl:0
	v_fmac_f32_dpp v54, v50, v14 row_shl:15 row_mask:0xf bank_mask:0xf bound_ctrl:0
	v_fmac_f32_dpp v6, v66, v26 row_shl:1 row_mask:0xf bank_mask:0xf bound_ctrl:0
	v_fmac_f32_dpp v41, v95, v19 row_shl:1 row_mask:0xf bank_mask:0xf bound_ctrl:0
	v_fmac_f32_dpp v39, v97, v27 row_shl:1 row_mask:0xf bank_mask:0xf bound_ctrl:0
	v_fmac_f32_dpp v47, v97, v15 row_shl:15 row_mask:0xf bank_mask:0xf bound_ctrl:0
	v_fmac_f32_dpp v55, v51, v15 row_shl:15 row_mask:0xf bank_mask:0xf bound_ctrl:0
	v_fmac_f32_dpp v7, v67, v27 row_shl:1 row_mask:0xf bank_mask:0xf bound_ctrl:0
	s_nop 0
	v_fmac_f32_dpp v40, v58, v18 row_shr:15 row_mask:0xf bank_mask:0xf bound_ctrl:0
; __device__ __forceinline__ unsigned cvtpk(float lo, float hi) { f32x2 v = {lo, hi}; bf16x2_t b = __builtin_convertvector(v, bf16x2_t); return __builtin_bit_cast(unsigned, b); }
; __device__ __forceinline__ float fast_exp2(float x) { return __builtin_amdgcn_exp2f(x); }
; __device__ __forceinline__ float fast_rcp(float x) { return __builtin_amdgcn_rcpf(x); }
;     __device__ __forceinline__ void operator()(AccRef acc, const Unit& u, int wr, int wc, int fr, int fq) const {
;     ...
;                 for (int i = 0; i < 4; ++i) {
;                     const float g0 = g0v[i], g1 = g1v[i], g2 = g2v[i], gb = gbv[i], h0 = h0v[i], h1 = h1v[i], h2 = h2v[i], hb = hbv[i];
;                     float gt[4], vl[4];
; #pragma unroll
;                     for (int m = 0; m < 4; ++m) { gt[m] = __builtin_fmaf(g1, acc[ai][0][m][n][i], gb); vl[m] = __builtin_fmaf(h1, acc[ai][1][m][n][i], hb); }
; #pragma unroll
;                     for (int m = 0; m < 4; ++m) {
;                         CONV_TAP(gt[m], acc[ai][0][m][n][i], g0, "row_shr:1"); CONV_TAP(gt[m], acc[ai][0][m][n][i], g2, "row_shl:1");
;                         CONV_TAP(vl[m], acc[ai][1][m][n][i], h0, "row_shr:1"); CONV_TAP(vl[m], acc[ai][1][m][n][i], h2, "row_shl:1");
;                         if (m > 0) { CONV_TAP(gt[m], acc[ai][0][m - 1][n][i], g0, "row_shl:15"); CONV_TAP(vl[m], acc[ai][1][m - 1][n][i], h0, "row_shl:15"); }
;                         if (m < 3) { CONV_TAP(gt[m], acc[ai][0][m + 1][n][i], g2, "row_shr:15"); CONV_TAP(vl[m], acc[ai][1][m + 1][n][i], h2, "row_shr:15"); }
;                     }
; #pragma unroll
;                     for (int m = 0; m < 4; ++m) {
;                         const float sg = gt[m] * fast_rcp(1.f + fast_exp2(-LOG2E * gt[m]));
;                         const float rv = sg * vl[m];
;                         if (i & 1) wpk[m][i >> 1] = cvtpk(rlo[m], rv); else rlo[m] = rv;
;                     }
;                     asm volatile("" ::: "memory");
;                 }
; #pragma unroll
;                 for (int m = 0; m < 4; ++m) { u32x2 w; w.x = wpk[m][0]; w.y = wpk[m][1];
;                     *(u32x2*)(ACT + (size_t)(row0 + ai * 128 + m * 16) * DFF + gcol + 4 * n) = w; }
;                 asm volatile("" ::: "memory");
;             }
;         }
	v_fmac_f32_dpp v38, v50, v26 row_shr:15 row_mask:0xf bank_mask:0xf bound_ctrl:0
	v_fmac_f32_dpp v48, v42, v18 row_shr:15 row_mask:0xf bank_mask:0xf bound_ctrl:0
	v_fmac_f32_dpp v46, v34, v26 row_shr:15 row_mask:0xf bank_mask:0xf bound_ctrl:0
	v_fmac_f32_dpp v56, v74, v18 row_shr:15 row_mask:0xf bank_mask:0xf bound_ctrl:0
	v_fmac_f32_dpp v54, v66, v26 row_shr:15 row_mask:0xf bank_mask:0xf bound_ctrl:0
	v_fmac_f32_dpp v6, v34, v14 row_shl:15 row_mask:0xf bank_mask:0xf bound_ctrl:0
	v_fmac_f32_dpp v41, v59, v19 row_shr:15 row_mask:0xf bank_mask:0xf bound_ctrl:0
	v_fmac_f32_dpp v39, v51, v27 row_shr:15 row_mask:0xf bank_mask:0xf bound_ctrl:0
	v_fmac_f32_dpp v49, v43, v19 row_shr:15 row_mask:0xf bank_mask:0xf bound_ctrl:0
	v_fmac_f32_dpp v47, v35, v27 row_shr:15 row_mask:0xf bank_mask:0xf bound_ctrl:0
	v_fmac_f32_dpp v57, v75, v19 row_shr:15 row_mask:0xf bank_mask:0xf bound_ctrl:0
	v_fmac_f32_dpp v55, v67, v27 row_shr:15 row_mask:0xf bank_mask:0xf bound_ctrl:0
	v_fmac_f32_dpp v7, v35, v15 row_shl:15 row_mask:0xf bank_mask:0xf bound_ctrl:0
	v_fma_f32 v14, v32, v90, v8
	v_fma_f32 v18, v32, v52, v8
	v_fma_f32 v26, v32, v36, v8
	v_fma_f32 v8, v32, v68, v8
	v_fma_f32 v15, v33, v91, v9
	v_fma_f32 v19, v33, v53, v9
	v_fma_f32 v27, v33, v37, v9
	v_fmac_f32_e32 v9, v33, v69
	v_fmac_f32_dpp v8, v68, v16 row_shr:1 row_mask:0xf bank_mask:0xf bound_ctrl:0
	v_fmac_f32_dpp v9, v69, v17 row_shr:1 row_mask:0xf bank_mask:0xf bound_ctrl:0
	v_pk_mul_f32 v[4:5], v[4:5], v[12:13]
	v_fmac_f32_dpp v8, v68, v28 row_shl:1 row_mask:0xf bank_mask:0xf bound_ctrl:0
	v_fmac_f32_dpp v9, v69, v29 row_shl:1 row_mask:0xf bank_mask:0xf bound_ctrl:0
	v_fmac_f32_dpp v30, v76, v20 row_shr:15 row_mask:0xf bank_mask:0xf bound_ctrl:0
	v_fmac_f32_dpp v22, v44, v20 row_shr:15 row_mask:0xf bank_mask:0xf bound_ctrl:0
	v_fmac_f32_dpp v10, v92, v20 row_shl:1 row_mask:0xf bank_mask:0xf bound_ctrl:0
	v_fmac_f32_dpp v18, v52, v16 row_shr:1 row_mask:0xf bank_mask:0xf bound_ctrl:0
	s_nop 0
	v_fmac_f32_dpp v8, v36, v16 row_shl:15 row_mask:0xf bank_mask:0xf bound_ctrl:0
	v_fmac_f32_dpp v9, v37, v17 row_shl:15 row_mask:0xf bank_mask:0xf bound_ctrl:0
	v_fmac_f32_dpp v26, v36, v16 row_shr:1 row_mask:0xf bank_mask:0xf bound_ctrl:0
	v_fmac_f32_dpp v14, v90, v16 row_shr:1 row_mask:0xf bank_mask:0xf bound_ctrl:0
	v_fmac_f32_dpp v10, v60, v20 row_shr:15 row_mask:0xf bank_mask:0xf bound_ctrl:0
	v_fmac_f32_dpp v18, v52, v28 row_shl:1 row_mask:0xf bank_mask:0xf bound_ctrl:0
	v_fmac_f32_dpp v31, v77, v21 row_shr:15 row_mask:0xf bank_mask:0xf bound_ctrl:0
	s_nop 0
	v_pk_mul_f32 v[4:5], v[8:9], v[4:5]
	v_fmac_f32_dpp v26, v36, v28 row_shl:1 row_mask:0xf bank_mask:0xf bound_ctrl:0
	v_fmac_f32_dpp v18, v90, v16 row_shl:15 row_mask:0xf bank_mask:0xf bound_ctrl:0
	v_fmac_f32_dpp v23, v45, v21 row_shr:15 row_mask:0xf bank_mask:0xf bound_ctrl:0
	v_fmac_f32_dpp v11, v93, v21 row_shl:1 row_mask:0xf bank_mask:0xf bound_ctrl:0
	v_fmac_f32_dpp v19, v53, v17 row_shr:1 row_mask:0xf bank_mask:0xf bound_ctrl:0
	s_nop 0
	v_cvt_pk_bf16_f32 v5, v4, v5
	v_mul_f32_e32 v4, 0xbfb8aa3b, v30
	v_exp_f32_e32 v4, v4
	v_fmac_f32_dpp v26, v52, v16 row_shl:15 row_mask:0xf bank_mask:0xf bound_ctrl:0
	v_fmac_f32_dpp v11, v61, v21 row_shr:15 row_mask:0xf bank_mask:0xf bound_ctrl:0
	v_fmac_f32_dpp v27, v37, v17 row_shr:1 row_mask:0xf bank_mask:0xf bound_ctrl:0
	v_fmac_f32_dpp v19, v53, v29 row_shl:1 row_mask:0xf bank_mask:0xf bound_ctrl:0
	v_fmac_f32_dpp v15, v91, v17 row_shr:1 row_mask:0xf bank_mask:0xf bound_ctrl:0
	s_nop 0
	v_add_f32_e32 v4, 1.0, v4
	v_rcp_f32_e32 v8, v4
	v_mul_f32_e32 v4, 0xbfb8aa3b, v22
	v_exp_f32_e32 v4, v4
	v_fmac_f32_dpp v27, v37, v29 row_shl:1 row_mask:0xf bank_mask:0xf bound_ctrl:0
	v_fmac_f32_dpp v19, v91, v17 row_shl:15 row_mask:0xf bank_mask:0xf bound_ctrl:0
	v_fmac_f32_dpp v14, v90, v28 row_shl:1 row_mask:0xf bank_mask:0xf bound_ctrl:0
	v_fmac_f32_dpp v15, v91, v29 row_shl:1 row_mask:0xf bank_mask:0xf bound_ctrl:0
	v_fmac_f32_dpp v18, v36, v28 row_shr:15 row_mask:0xf bank_mask:0xf bound_ctrl:0
	s_nop 0
	v_add_f32_e32 v4, 1.0, v4
	v_rcp_f32_e32 v12, v4
	v_mul_f32_e32 v4, 0xbfb8aa3b, v10
	v_exp_f32_e32 v4, v4
	v_fmac_f32_dpp v27, v53, v17 row_shl:15 row_mask:0xf bank_mask:0xf bound_ctrl:0
	v_fmac_f32_dpp v14, v52, v28 row_shr:15 row_mask:0xf bank_mask:0xf bound_ctrl:0
	v_fmac_f32_dpp v15, v53, v29 row_shr:15 row_mask:0xf bank_mask:0xf bound_ctrl:0
	v_fmac_f32_dpp v19, v37, v29 row_shr:15 row_mask:0xf bank_mask:0xf bound_ctrl:0
	v_fmac_f32_dpp v26, v68, v28 row_shr:15 row_mask:0xf bank_mask:0xf bound_ctrl:0
	s_nop 0
	v_add_f32_e32 v4, 1.0, v4
	v_rcp_f32_e32 v16, v4
	v_mul_f32_e32 v4, 0xbfb8aa3b, v31
	v_exp_f32_e32 v4, v4
	v_fmac_f32_dpp v27, v69, v29 row_shr:15 row_mask:0xf bank_mask:0xf bound_ctrl:0
	s_nop 0
	v_add_f32_e32 v4, 1.0, v4
	v_rcp_f32_e32 v9, v4
	v_mul_f32_e32 v4, 0xbfb8aa3b, v23
	v_exp_f32_e32 v4, v4
	v_pk_mul_f32 v[8:9], v[30:31], v[8:9]
	v_add_f32_e32 v4, 1.0, v4
	v_rcp_f32_e32 v13, v4
	v_mul_f32_e32 v4, 0xbfb8aa3b, v11
	v_exp_f32_e32 v4, v4
	v_pk_mul_f32 v[8:9], v[26:27], v[8:9]
	v_pk_mul_f32 v[12:13], v[22:23], v[12:13]
	v_cvt_pk_bf16_f32 v9, v8, v9
	v_add_f32_e32 v4, 1.0, v4
	v_rcp_f32_e32 v17, v4
	v_mul_f32_e32 v4, 0xbfb8aa3b, v2
	v_exp_f32_e32 v4, v4
	v_pk_mul_f32 v[12:13], v[18:19], v[12:13]
	v_pk_mul_f32 v[10:11], v[10:11], v[16:17]
	v_cvt_pk_bf16_f32 v13, v12, v13
	v_add_f32_e32 v4, 1.0, v4
	v_pk_mul_f32 v[10:11], v[14:15], v[10:11]
	v_rcp_f32_e32 v14, v4
	v_mul_f32_e32 v4, 0xbfb8aa3b, v56
	v_exp_f32_e32 v4, v4
	v_cvt_pk_bf16_f32 v11, v10, v11
	v_add_f32_e32 v4, 1.0, v4
	v_rcp_f32_e32 v16, v4
	v_mul_f32_e32 v4, 0xbfb8aa3b, v48
	v_exp_f32_e32 v4, v4
	s_nop 0
	v_add_f32_e32 v4, 1.0, v4
	v_rcp_f32_e32 v18, v4
	v_mul_f32_e32 v4, 0xbfb8aa3b, v40
	v_exp_f32_e32 v4, v4
	s_nop 0
	v_add_f32_e32 v4, 1.0, v4
	v_rcp_f32_e32 v20, v4
	v_mul_f32_e32 v4, 0xbfb8aa3b, v3
	v_exp_f32_e32 v4, v4
	s_nop 0
	v_add_f32_e32 v4, 1.0, v4
	v_rcp_f32_e32 v15, v4
	s_nop 0
	v_pk_mul_f32 v[2:3], v[2:3], v[14:15]
	s_nop 0
	v_pk_mul_f32 v[2:3], v[6:7], v[2:3]
	s_nop 0
	v_cvt_pk_bf16_f32 v4, v2, v3
	v_mul_f32_e32 v2, 0xbfb8aa3b, v57
	v_exp_f32_e32 v2, v2
	s_nop 0
	v_add_f32_e32 v2, 1.0, v2
	v_rcp_f32_e32 v17, v2
	s_nop 0
	v_pk_mul_f32 v[2:3], v[56:57], v[16:17]
	s_nop 0
	v_pk_mul_f32 v[2:3], v[54:55], v[2:3]
	s_nop 0
	v_cvt_pk_bf16_f32 v8, v2, v3
	v_mul_f32_e32 v2, 0xbfb8aa3b, v49
	v_exp_f32_e32 v2, v2
	s_nop 0
	v_add_f32_e32 v2, 1.0, v2
	v_rcp_f32_e32 v19, v2
	s_nop 0
	v_pk_mul_f32 v[2:3], v[48:49], v[18:19]
	s_nop 0
	v_pk_mul_f32 v[2:3], v[46:47], v[2:3]
	s_nop 0
	v_cvt_pk_bf16_f32 v12, v2, v3
	v_mul_f32_e32 v2, 0xbfb8aa3b, v41
	v_exp_f32_e32 v2, v2
	s_nop 0
	v_add_f32_e32 v2, 1.0, v2
	v_rcp_f32_e32 v21, v2
	s_nop 0
	v_pk_mul_f32 v[2:3], v[40:41], v[20:21]
	s_nop 0
	v_pk_mul_f32 v[2:3], v[38:39], v[2:3]
	s_nop 0
	v_cvt_pk_bf16_f32 v10, v2, v3
	global_store_dwordx2 v[80:81], v[10:11], off offset:8
	global_store_dwordx2 v[82:83], v[12:13], off offset:8
	global_store_dwordx2 v[102:103], v[8:9], off offset:8
	global_store_dwordx2 v[104:105], v[4:5], off offset:8
	s_cbranch_vccnz .LBB0_783
; #define PG8_BAR __builtin_amdgcn_s_barrier()
; template <class Epi>
; __device__ __forceinline__ void gemm_phase(LAS unsigned char* lds, const Gemm g, const Epi& E) {
;     ...
;         cur = nxt; cA = nA; cB = nB; ++ui;
;         if (wr == 1) PG8_BAR;
;     }
	v_readlane_b32 s20, v252, 47
	v_readlane_b32 s21, v252, 48
	s_andn2_b64 vcc, exec, s[20:21]
	s_cbranch_vccnz .LBB0_782
	s_barrier
	s_branch .LBB0_782
